# attention sample rows: P.V loop batched (64 loads in flight), q.k loops unrolled x4 with 16 loads in flight
# speedup vs baseline: 1.0718x; 1.0027x over previous
; #define LAS __attribute__((address_space(3)))
; DI void attn_sample_task(LAS unsigned char* wl, int task, int l, ArgsP a, const bf16_t* Q, bf16_t* YB, int lane) {
;     ...
;     for (int rr = 0; rr < 3; ++rr) { const int j = rr * 64 + lane; float s[4] = {0.f, 0.f, 0.f, 0.f};
;         if (j < 132) { const float* kp = j < 128 ? ck + (size_t)j * 128 : nk + (size_t)(j - 128) * 128;
; #pragma unroll 4
;             for (int d4 = 0; d4 < 16; ++d4) { const f32x4 k4 = *(const f32x4*)(kp + 4 * d4);
; #pragma unroll
;                 for (int t = 0; t < 4; ++t) { const f32x4 q4 = *(const LAS f32x4*)(qs + t * 64 + 4 * d4); s[t] += k4[0] * q4[0] + k4[1] * q4[1] + k4[2] * q4[2] + k4[3] * q4[3]; } } }
.LBB0_969:
	global_load_dwordx4 v[198:201], v[2:3], off offset:16
	global_load_dwordx4 v[202:205], v[2:3], off
	global_load_dwordx4 v[206:209], v[2:3], off offset:-16
	global_load_dwordx4 v[210:213], v[2:3], off offset:-32
	global_load_dwordx4 v[214:217], v[2:3], off offset:80
	global_load_dwordx4 v[218:221], v[2:3], off offset:64
	global_load_dwordx4 v[222:225], v[2:3], off offset:48
	global_load_dwordx4 v[226:229], v[2:3], off offset:32
	global_load_dwordx4 v[230:233], v[2:3], off offset:144
	global_load_dwordx4 v[234:237], v[2:3], off offset:128
	global_load_dwordx4 v[238:241], v[2:3], off offset:112
	global_load_dwordx4 v[242:245], v[2:3], off offset:96
	global_load_dwordx4 v[32:35], v[2:3], off offset:208
	global_load_dwordx4 v[36:39], v[2:3], off offset:192
	global_load_dwordx4 v[48:51], v[2:3], off offset:176
	global_load_dwordx4 v[54:57], v[2:3], off offset:160
	v_add_u32_e32 v42, s2, v43
	ds_read_b128 v[60:63], v42
	ds_read_b128 v[70:73], v42 offset:16
	ds_read_b128 v[74:77], v42 offset:32
	ds_read_b128 v[78:81], v42 offset:48
	ds_read_b128 v[82:85], v42 offset:256
	s_add_i32 s2, s2, 64
	s_waitcnt lgkmcnt(0)
	v_pk_mov_b32 v[44:45], v[60:61], v[82:83] op_sel:[1,0]
	v_mov_b32_e32 v61, v83
	s_waitcnt vmcnt(12)
	v_pk_mul_f32 v[60:61], v[210:211], v[60:61]
	s_nop 0
	v_pk_fma_f32 v[44:45], v[210:211], v[44:45], v[60:61] op_sel:[1,0,0] op_sel_hi:[0,1,1]
	v_mov_b32_e32 v60, v62
	v_mov_b32_e32 v61, v84
	v_pk_fma_f32 v[44:45], v[212:213], v[60:61], v[44:45] op_sel_hi:[0,1,1]
	v_mov_b32_e32 v84, v63
	ds_read_b128 v[60:63], v42 offset:512
	v_mov_b32_e32 v40, v213
	v_pk_fma_f32 v[44:45], v[40:41], v[84:85], v[44:45] op_sel_hi:[0,1,1]
	v_pk_add_f32 v[44:45], v[4:5], v[44:45]
	s_waitcnt lgkmcnt(0)
	v_mul_f32_e32 v4, v211, v61
	v_pk_fma_f32 v[4:5], v[210:211], v[60:61], v[4:5] op_sel_hi:[1,1,0]
	v_mul_f32_e32 v82, v212, v62
	v_mul_f32_e32 v84, v213, v63
	ds_read_b128 v[60:63], v42 offset:768
	s_waitcnt lgkmcnt(0)
	v_mul_f32_e32 v40, v210, v60
	v_pk_mul_f32 v[212:213], v[212:213], v[62:63]
	v_pk_fma_f32 v[210:211], v[210:211], v[60:61], v[40:41] op_sel_hi:[1,1,0]
	v_mov_b32_e32 v5, v212
	v_mov_b32_e32 v83, v211
	v_pk_add_f32 v[4:5], v[4:5], v[82:83]
	v_mov_b32_e32 v85, v213
	v_pk_add_f32 v[4:5], v[84:85], v[4:5]
	v_mov_b32_e32 v40, v209
	v_pk_add_f32 v[210:211], v[6:7], v[4:5]
	ds_read_b128 v[4:7], v42 offset:272
	s_waitcnt lgkmcnt(0)
	v_pk_mov_b32 v[212:213], v[70:71], v[4:5] op_sel:[1,0]
	v_mov_b32_e32 v71, v5
	v_pk_mul_f32 v[4:5], v[206:207], v[70:71]
	s_nop 0
	v_pk_fma_f32 v[4:5], v[206:207], v[212:213], v[4:5] op_sel:[1,0,0] op_sel_hi:[0,1,1]
	v_mov_b32_e32 v212, v72
	v_mov_b32_e32 v213, v6
	v_pk_fma_f32 v[4:5], v[208:209], v[212:213], v[4:5] op_sel_hi:[0,1,1]
	v_mov_b32_e32 v6, v73
	v_pk_fma_f32 v[4:5], v[40:41], v[6:7], v[4:5] op_sel_hi:[0,1,1]
	v_pk_add_f32 v[44:45], v[44:45], v[4:5]
	ds_read_b128 v[4:7], v42 offset:528
	s_waitcnt lgkmcnt(0)
	v_mul_f32_e32 v40, v207, v5
	v_pk_fma_f32 v[212:213], v[206:207], v[4:5], v[40:41] op_sel_hi:[1,1,0]
	v_mul_f32_e32 v60, v208, v6
	v_mul_f32_e32 v62, v209, v7
	ds_read_b128 v[4:7], v42 offset:784
	s_waitcnt lgkmcnt(0)
	v_mul_f32_e32 v40, v206, v4
	v_pk_mul_f32 v[6:7], v[208:209], v[6:7]
	v_pk_fma_f32 v[4:5], v[206:207], v[4:5], v[40:41] op_sel_hi:[1,1,0]
	v_mov_b32_e32 v213, v6
	v_mov_b32_e32 v61, v5
	v_pk_add_f32 v[4:5], v[212:213], v[60:61]
	v_mov_b32_e32 v63, v7
	v_pk_add_f32 v[4:5], v[62:63], v[4:5]
	v_mov_b32_e32 v40, v205
	v_pk_add_f32 v[206:207], v[210:211], v[4:5]
	ds_read_b128 v[4:7], v42 offset:288
	s_waitcnt lgkmcnt(0)
	v_pk_mov_b32 v[208:209], v[74:75], v[4:5] op_sel:[1,0]
	v_mov_b32_e32 v75, v5
	v_pk_mul_f32 v[4:5], v[202:203], v[74:75]
	s_nop 0
	v_pk_fma_f32 v[4:5], v[202:203], v[208:209], v[4:5] op_sel:[1,0,0] op_sel_hi:[0,1,1]
	v_mov_b32_e32 v208, v76
	v_mov_b32_e32 v209, v6
	v_pk_fma_f32 v[4:5], v[204:205], v[208:209], v[4:5] op_sel_hi:[0,1,1]
	v_mov_b32_e32 v6, v77
	v_pk_fma_f32 v[4:5], v[40:41], v[6:7], v[4:5] op_sel_hi:[0,1,1]
	v_pk_add_f32 v[44:45], v[44:45], v[4:5]
	ds_read_b128 v[4:7], v42 offset:544
	s_waitcnt lgkmcnt(0)
	v_mul_f32_e32 v40, v203, v5
	v_pk_fma_f32 v[208:209], v[202:203], v[4:5], v[40:41] op_sel_hi:[1,1,0]
	v_mul_f32_e32 v210, v204, v6
	v_mul_f32_e32 v212, v205, v7
	ds_read_b128 v[4:7], v42 offset:800
	s_waitcnt lgkmcnt(0)
	v_pk_mul_f32 v[6:7], v[204:205], v[6:7]
	v_mul_f32_e32 v204, v202, v4
	v_pk_fma_f32 v[4:5], v[202:203], v[4:5], v[204:205] op_sel_hi:[1,1,0]
	v_mov_b32_e32 v209, v6
	v_mov_b32_e32 v211, v5
	v_pk_add_f32 v[4:5], v[208:209], v[210:211]
	v_mov_b32_e32 v213, v7
	v_pk_add_f32 v[4:5], v[212:213], v[4:5]
	s_nop 0
	v_pk_add_f32 v[206:207], v[206:207], v[4:5]
	ds_read_b128 v[4:7], v42 offset:304
	s_waitcnt lgkmcnt(0)
	v_pk_mov_b32 v[202:203], v[78:79], v[4:5] op_sel:[1,0]
	v_mov_b32_e32 v79, v5
	v_pk_mul_f32 v[4:5], v[198:199], v[78:79]
	s_nop 0
	v_pk_fma_f32 v[4:5], v[198:199], v[202:203], v[4:5] op_sel:[1,0,0] op_sel_hi:[0,1,1]
	v_mov_b32_e32 v202, v80
	v_mov_b32_e32 v203, v6
	v_pk_fma_f32 v[4:5], v[200:201], v[202:203], v[4:5] op_sel_hi:[0,1,1]
	v_mov_b32_e32 v202, v201
	v_mov_b32_e32 v6, v81
	v_pk_fma_f32 v[4:5], v[202:203], v[6:7], v[4:5] op_sel_hi:[0,1,1]
	ds_read_b128 v[202:205], v42 offset:560
	v_pk_add_f32 v[4:5], v[44:45], v[4:5]
	s_waitcnt lgkmcnt(0)
	v_mul_f32_e32 v6, v199, v203
	v_pk_fma_f32 v[6:7], v[198:199], v[202:203], v[6:7] op_sel_hi:[1,1,0]
	v_mul_f32_e32 v44, v200, v204
	v_mul_f32_e32 v208, v201, v205
	ds_read_b128 v[202:205], v42 offset:816
	s_waitcnt lgkmcnt(0)
; #define LAS __attribute__((address_space(3)))
; DI void attn_sample_task(LAS unsigned char* wl, int task, int l, ArgsP a, const bf16_t* Q, bf16_t* YB, int lane) {
;     ...
;     for (int rr = 0; rr < 3; ++rr) { const int j = rr * 64 + lane; float s[4] = {0.f, 0.f, 0.f, 0.f};
;         if (j < 132) { const float* kp = j < 128 ? ck + (size_t)j * 128 : nk + (size_t)(j - 128) * 128;
; #pragma unroll 4
;             for (int d4 = 0; d4 < 16; ++d4) { const f32x4 k4 = *(const f32x4*)(kp + 4 * d4);
; #pragma unroll
;                 for (int t = 0; t < 4; ++t) { const f32x4 q4 = *(const LAS f32x4*)(qs + t * 64 + 4 * d4); s[t] += k4[0] * q4[0] + k4[1] * q4[1] + k4[2] * q4[2] + k4[3] * q4[3]; } } }
	v_pk_mul_f32 v[200:201], v[200:201], v[204:205]
	v_mul_f32_e32 v204, v198, v202
	v_pk_fma_f32 v[198:199], v[198:199], v[202:203], v[204:205] op_sel_hi:[1,1,0]
	v_mov_b32_e32 v7, v200
	v_mov_b32_e32 v45, v199
	v_pk_add_f32 v[6:7], v[6:7], v[44:45]
	v_mov_b32_e32 v209, v201
	v_pk_add_f32 v[6:7], v[208:209], v[6:7]
	s_nop 0
	v_pk_add_f32 v[6:7], v[206:207], v[6:7]
	v_add_u32_e32 v42, s2, v43
	ds_read_b128 v[60:63], v42
	ds_read_b128 v[70:73], v42 offset:16
	ds_read_b128 v[74:77], v42 offset:32
	ds_read_b128 v[78:81], v42 offset:48
	ds_read_b128 v[82:85], v42 offset:256
	s_add_i32 s2, s2, 64
	s_waitcnt lgkmcnt(0)
	v_pk_mov_b32 v[44:45], v[60:61], v[82:83] op_sel:[1,0]
	v_mov_b32_e32 v61, v83
	s_waitcnt vmcnt(8)
	v_pk_mul_f32 v[60:61], v[226:227], v[60:61]
	s_nop 0
	v_pk_fma_f32 v[44:45], v[226:227], v[44:45], v[60:61] op_sel:[1,0,0] op_sel_hi:[0,1,1]
	v_mov_b32_e32 v60, v62
	v_mov_b32_e32 v61, v84
	v_pk_fma_f32 v[44:45], v[228:229], v[60:61], v[44:45] op_sel_hi:[0,1,1]
	v_mov_b32_e32 v84, v63
	ds_read_b128 v[60:63], v42 offset:512
	v_mov_b32_e32 v40, v229
	v_pk_fma_f32 v[44:45], v[40:41], v[84:85], v[44:45] op_sel_hi:[0,1,1]
	v_pk_add_f32 v[44:45], v[4:5], v[44:45]
	s_waitcnt lgkmcnt(0)
	v_mul_f32_e32 v4, v227, v61
	v_pk_fma_f32 v[4:5], v[226:227], v[60:61], v[4:5] op_sel_hi:[1,1,0]
	v_mul_f32_e32 v82, v228, v62
	v_mul_f32_e32 v84, v229, v63
	ds_read_b128 v[60:63], v42 offset:768
	s_waitcnt lgkmcnt(0)
	v_mul_f32_e32 v40, v226, v60
	v_pk_mul_f32 v[228:229], v[228:229], v[62:63]
	v_pk_fma_f32 v[226:227], v[226:227], v[60:61], v[40:41] op_sel_hi:[1,1,0]
	v_mov_b32_e32 v5, v228
	v_mov_b32_e32 v83, v227
	v_pk_add_f32 v[4:5], v[4:5], v[82:83]
	v_mov_b32_e32 v85, v229
	v_pk_add_f32 v[4:5], v[84:85], v[4:5]
	v_mov_b32_e32 v40, v225
	v_pk_add_f32 v[226:227], v[6:7], v[4:5]
	ds_read_b128 v[4:7], v42 offset:272
	s_waitcnt lgkmcnt(0)
	v_pk_mov_b32 v[228:229], v[70:71], v[4:5] op_sel:[1,0]
	v_mov_b32_e32 v71, v5
	v_pk_mul_f32 v[4:5], v[222:223], v[70:71]
	s_nop 0
	v_pk_fma_f32 v[4:5], v[222:223], v[228:229], v[4:5] op_sel:[1,0,0] op_sel_hi:[0,1,1]
	v_mov_b32_e32 v228, v72
	v_mov_b32_e32 v229, v6
	v_pk_fma_f32 v[4:5], v[224:225], v[228:229], v[4:5] op_sel_hi:[0,1,1]
	v_mov_b32_e32 v6, v73
	v_pk_fma_f32 v[4:5], v[40:41], v[6:7], v[4:5] op_sel_hi:[0,1,1]
	v_pk_add_f32 v[44:45], v[44:45], v[4:5]
	ds_read_b128 v[4:7], v42 offset:528
	s_waitcnt lgkmcnt(0)
	v_mul_f32_e32 v40, v223, v5
	v_pk_fma_f32 v[228:229], v[222:223], v[4:5], v[40:41] op_sel_hi:[1,1,0]
	v_mul_f32_e32 v60, v224, v6
	v_mul_f32_e32 v62, v225, v7
	ds_read_b128 v[4:7], v42 offset:784
	s_waitcnt lgkmcnt(0)
	v_mul_f32_e32 v40, v222, v4
	v_pk_mul_f32 v[6:7], v[224:225], v[6:7]
	v_pk_fma_f32 v[4:5], v[222:223], v[4:5], v[40:41] op_sel_hi:[1,1,0]
	v_mov_b32_e32 v229, v6
	v_mov_b32_e32 v61, v5
	v_pk_add_f32 v[4:5], v[228:229], v[60:61]
	v_mov_b32_e32 v63, v7
	v_pk_add_f32 v[4:5], v[62:63], v[4:5]
	v_mov_b32_e32 v40, v221
	v_pk_add_f32 v[222:223], v[226:227], v[4:5]
	ds_read_b128 v[4:7], v42 offset:288
	s_waitcnt lgkmcnt(0)
	v_pk_mov_b32 v[224:225], v[74:75], v[4:5] op_sel:[1,0]
	v_mov_b32_e32 v75, v5
	v_pk_mul_f32 v[4:5], v[218:219], v[74:75]
	s_nop 0
	v_pk_fma_f32 v[4:5], v[218:219], v[224:225], v[4:5] op_sel:[1,0,0] op_sel_hi:[0,1,1]
	v_mov_b32_e32 v224, v76
	v_mov_b32_e32 v225, v6
	v_pk_fma_f32 v[4:5], v[220:221], v[224:225], v[4:5] op_sel_hi:[0,1,1]
	v_mov_b32_e32 v6, v77
	v_pk_fma_f32 v[4:5], v[40:41], v[6:7], v[4:5] op_sel_hi:[0,1,1]
	v_pk_add_f32 v[44:45], v[44:45], v[4:5]
	ds_read_b128 v[4:7], v42 offset:544
	s_waitcnt lgkmcnt(0)
	v_mul_f32_e32 v40, v219, v5
	v_pk_fma_f32 v[224:225], v[218:219], v[4:5], v[40:41] op_sel_hi:[1,1,0]
	v_mul_f32_e32 v226, v220, v6
	v_mul_f32_e32 v228, v221, v7
	ds_read_b128 v[4:7], v42 offset:800
	s_waitcnt lgkmcnt(0)
	v_pk_mul_f32 v[6:7], v[220:221], v[6:7]
	v_mul_f32_e32 v220, v218, v4
	v_pk_fma_f32 v[4:5], v[218:219], v[4:5], v[220:221] op_sel_hi:[1,1,0]
	v_mov_b32_e32 v225, v6
	v_mov_b32_e32 v227, v5
	v_pk_add_f32 v[4:5], v[224:225], v[226:227]
	v_mov_b32_e32 v229, v7
	v_pk_add_f32 v[4:5], v[228:229], v[4:5]
	s_nop 0
	v_pk_add_f32 v[222:223], v[222:223], v[4:5]
	ds_read_b128 v[4:7], v42 offset:304
	s_waitcnt lgkmcnt(0)
	v_pk_mov_b32 v[218:219], v[78:79], v[4:5] op_sel:[1,0]
	v_mov_b32_e32 v79, v5
	v_pk_mul_f32 v[4:5], v[214:215], v[78:79]
	s_nop 0
	v_pk_fma_f32 v[4:5], v[214:215], v[218:219], v[4:5] op_sel:[1,0,0] op_sel_hi:[0,1,1]
	v_mov_b32_e32 v218, v80
	v_mov_b32_e32 v219, v6
	v_pk_fma_f32 v[4:5], v[216:217], v[218:219], v[4:5] op_sel_hi:[0,1,1]
	v_mov_b32_e32 v218, v217
	v_mov_b32_e32 v6, v81
	v_pk_fma_f32 v[4:5], v[218:219], v[6:7], v[4:5] op_sel_hi:[0,1,1]
	ds_read_b128 v[218:221], v42 offset:560
	v_pk_add_f32 v[4:5], v[44:45], v[4:5]
	s_waitcnt lgkmcnt(0)
	v_mul_f32_e32 v6, v215, v219
	v_pk_fma_f32 v[6:7], v[214:215], v[218:219], v[6:7] op_sel_hi:[1,1,0]
	v_mul_f32_e32 v44, v216, v220
	v_mul_f32_e32 v224, v217, v221
	ds_read_b128 v[218:221], v42 offset:816
	s_waitcnt lgkmcnt(0)
	v_pk_mul_f32 v[216:217], v[216:217], v[220:221]
	v_mul_f32_e32 v220, v214, v218
	v_pk_fma_f32 v[214:215], v[214:215], v[218:219], v[220:221] op_sel_hi:[1,1,0]
	v_mov_b32_e32 v7, v216
	v_mov_b32_e32 v45, v215
	v_pk_add_f32 v[6:7], v[6:7], v[44:45]
	v_mov_b32_e32 v225, v217
	v_pk_add_f32 v[6:7], v[224:225], v[6:7]
	s_nop 0
	v_pk_add_f32 v[6:7], v[222:223], v[6:7]
	v_add_u32_e32 v42, s2, v43
	ds_read_b128 v[60:63], v42
	ds_read_b128 v[70:73], v42 offset:16
	ds_read_b128 v[74:77], v42 offset:32
	ds_read_b128 v[78:81], v42 offset:48
	ds_read_b128 v[82:85], v42 offset:256
	s_add_i32 s2, s2, 64
	s_waitcnt lgkmcnt(0)
	v_pk_mov_b32 v[44:45], v[60:61], v[82:83] op_sel:[1,0]
	v_mov_b32_e32 v61, v83
	s_waitcnt vmcnt(4)
; #define LAS __attribute__((address_space(3)))
; DI void attn_sample_task(LAS unsigned char* wl, int task, int l, ArgsP a, const bf16_t* Q, bf16_t* YB, int lane) {
;     ...
;     for (int rr = 0; rr < 3; ++rr) { const int j = rr * 64 + lane; float s[4] = {0.f, 0.f, 0.f, 0.f};
;         if (j < 132) { const float* kp = j < 128 ? ck + (size_t)j * 128 : nk + (size_t)(j - 128) * 128;
; #pragma unroll 4
;             for (int d4 = 0; d4 < 16; ++d4) { const f32x4 k4 = *(const f32x4*)(kp + 4 * d4);
; #pragma unroll
;                 for (int t = 0; t < 4; ++t) { const f32x4 q4 = *(const LAS f32x4*)(qs + t * 64 + 4 * d4); s[t] += k4[0] * q4[0] + k4[1] * q4[1] + k4[2] * q4[2] + k4[3] * q4[3]; } } }
	v_pk_mul_f32 v[60:61], v[242:243], v[60:61]
	s_nop 0
	v_pk_fma_f32 v[44:45], v[242:243], v[44:45], v[60:61] op_sel:[1,0,0] op_sel_hi:[0,1,1]
	v_mov_b32_e32 v60, v62
	v_mov_b32_e32 v61, v84
	v_pk_fma_f32 v[44:45], v[244:245], v[60:61], v[44:45] op_sel_hi:[0,1,1]
	v_mov_b32_e32 v84, v63
	ds_read_b128 v[60:63], v42 offset:512
	v_mov_b32_e32 v40, v245
	v_pk_fma_f32 v[44:45], v[40:41], v[84:85], v[44:45] op_sel_hi:[0,1,1]
	v_pk_add_f32 v[44:45], v[4:5], v[44:45]
	s_waitcnt lgkmcnt(0)
	v_mul_f32_e32 v4, v243, v61
	v_pk_fma_f32 v[4:5], v[242:243], v[60:61], v[4:5] op_sel_hi:[1,1,0]
	v_mul_f32_e32 v82, v244, v62
	v_mul_f32_e32 v84, v245, v63
	ds_read_b128 v[60:63], v42 offset:768
	s_waitcnt lgkmcnt(0)
	v_mul_f32_e32 v40, v242, v60
	v_pk_mul_f32 v[244:245], v[244:245], v[62:63]
	v_pk_fma_f32 v[242:243], v[242:243], v[60:61], v[40:41] op_sel_hi:[1,1,0]
	v_mov_b32_e32 v5, v244
	v_mov_b32_e32 v83, v243
	v_pk_add_f32 v[4:5], v[4:5], v[82:83]
	v_mov_b32_e32 v85, v245
	v_pk_add_f32 v[4:5], v[84:85], v[4:5]
	v_mov_b32_e32 v40, v241
	v_pk_add_f32 v[242:243], v[6:7], v[4:5]
	ds_read_b128 v[4:7], v42 offset:272
	s_waitcnt lgkmcnt(0)
	v_pk_mov_b32 v[244:245], v[70:71], v[4:5] op_sel:[1,0]
	v_mov_b32_e32 v71, v5
	v_pk_mul_f32 v[4:5], v[238:239], v[70:71]
	s_nop 0
	v_pk_fma_f32 v[4:5], v[238:239], v[244:245], v[4:5] op_sel:[1,0,0] op_sel_hi:[0,1,1]
	v_mov_b32_e32 v244, v72
	v_mov_b32_e32 v245, v6
	v_pk_fma_f32 v[4:5], v[240:241], v[244:245], v[4:5] op_sel_hi:[0,1,1]
	v_mov_b32_e32 v6, v73
	v_pk_fma_f32 v[4:5], v[40:41], v[6:7], v[4:5] op_sel_hi:[0,1,1]
	v_pk_add_f32 v[44:45], v[44:45], v[4:5]
	ds_read_b128 v[4:7], v42 offset:528
	s_waitcnt lgkmcnt(0)
	v_mul_f32_e32 v40, v239, v5
	v_pk_fma_f32 v[244:245], v[238:239], v[4:5], v[40:41] op_sel_hi:[1,1,0]
	v_mul_f32_e32 v60, v240, v6
	v_mul_f32_e32 v62, v241, v7
	ds_read_b128 v[4:7], v42 offset:784
	s_waitcnt lgkmcnt(0)
	v_mul_f32_e32 v40, v238, v4
	v_pk_mul_f32 v[6:7], v[240:241], v[6:7]
	v_pk_fma_f32 v[4:5], v[238:239], v[4:5], v[40:41] op_sel_hi:[1,1,0]
	v_mov_b32_e32 v245, v6
	v_mov_b32_e32 v61, v5
	v_pk_add_f32 v[4:5], v[244:245], v[60:61]
	v_mov_b32_e32 v63, v7
	v_pk_add_f32 v[4:5], v[62:63], v[4:5]
	v_mov_b32_e32 v40, v237
	v_pk_add_f32 v[238:239], v[242:243], v[4:5]
	ds_read_b128 v[4:7], v42 offset:288
	s_waitcnt lgkmcnt(0)
	v_pk_mov_b32 v[240:241], v[74:75], v[4:5] op_sel:[1,0]
	v_mov_b32_e32 v75, v5
	v_pk_mul_f32 v[4:5], v[234:235], v[74:75]
	s_nop 0
	v_pk_fma_f32 v[4:5], v[234:235], v[240:241], v[4:5] op_sel:[1,0,0] op_sel_hi:[0,1,1]
	v_mov_b32_e32 v240, v76
	v_mov_b32_e32 v241, v6
	v_pk_fma_f32 v[4:5], v[236:237], v[240:241], v[4:5] op_sel_hi:[0,1,1]
	v_mov_b32_e32 v6, v77
	v_pk_fma_f32 v[4:5], v[40:41], v[6:7], v[4:5] op_sel_hi:[0,1,1]
	v_pk_add_f32 v[44:45], v[44:45], v[4:5]
	ds_read_b128 v[4:7], v42 offset:544
	s_waitcnt lgkmcnt(0)
	v_mul_f32_e32 v40, v235, v5
	v_pk_fma_f32 v[240:241], v[234:235], v[4:5], v[40:41] op_sel_hi:[1,1,0]
	v_mul_f32_e32 v242, v236, v6
	v_mul_f32_e32 v244, v237, v7
	ds_read_b128 v[4:7], v42 offset:800
	s_waitcnt lgkmcnt(0)
	v_pk_mul_f32 v[6:7], v[236:237], v[6:7]
	v_mul_f32_e32 v236, v234, v4
	v_pk_fma_f32 v[4:5], v[234:235], v[4:5], v[236:237] op_sel_hi:[1,1,0]
	v_mov_b32_e32 v241, v6
	v_mov_b32_e32 v243, v5
	v_pk_add_f32 v[4:5], v[240:241], v[242:243]
	v_mov_b32_e32 v245, v7
	v_pk_add_f32 v[4:5], v[244:245], v[4:5]
	s_nop 0
	v_pk_add_f32 v[238:239], v[238:239], v[4:5]
	ds_read_b128 v[4:7], v42 offset:304
	s_waitcnt lgkmcnt(0)
	v_pk_mov_b32 v[234:235], v[78:79], v[4:5] op_sel:[1,0]
	v_mov_b32_e32 v79, v5
	v_pk_mul_f32 v[4:5], v[230:231], v[78:79]
	s_nop 0
	v_pk_fma_f32 v[4:5], v[230:231], v[234:235], v[4:5] op_sel:[1,0,0] op_sel_hi:[0,1,1]
	v_mov_b32_e32 v234, v80
	v_mov_b32_e32 v235, v6
	v_pk_fma_f32 v[4:5], v[232:233], v[234:235], v[4:5] op_sel_hi:[0,1,1]
	v_mov_b32_e32 v234, v233
	v_mov_b32_e32 v6, v81
	v_pk_fma_f32 v[4:5], v[234:235], v[6:7], v[4:5] op_sel_hi:[0,1,1]
	ds_read_b128 v[234:237], v42 offset:560
	v_pk_add_f32 v[4:5], v[44:45], v[4:5]
	s_waitcnt lgkmcnt(0)
	v_mul_f32_e32 v6, v231, v235
	v_pk_fma_f32 v[6:7], v[230:231], v[234:235], v[6:7] op_sel_hi:[1,1,0]
	v_mul_f32_e32 v44, v232, v236
	v_mul_f32_e32 v240, v233, v237
	ds_read_b128 v[234:237], v42 offset:816
	s_waitcnt lgkmcnt(0)
	v_pk_mul_f32 v[232:233], v[232:233], v[236:237]
	v_mul_f32_e32 v236, v230, v234
	v_pk_fma_f32 v[230:231], v[230:231], v[234:235], v[236:237] op_sel_hi:[1,1,0]
	v_mov_b32_e32 v7, v232
	v_mov_b32_e32 v45, v231
	v_pk_add_f32 v[6:7], v[6:7], v[44:45]
	v_mov_b32_e32 v241, v233
	v_pk_add_f32 v[6:7], v[240:241], v[6:7]
	s_nop 0
	v_pk_add_f32 v[6:7], v[238:239], v[6:7]
	v_add_u32_e32 v42, s2, v43
	ds_read_b128 v[60:63], v42
	ds_read_b128 v[70:73], v42 offset:16
	ds_read_b128 v[74:77], v42 offset:32
	ds_read_b128 v[78:81], v42 offset:48
	ds_read_b128 v[82:85], v42 offset:256
	s_add_i32 s2, s2, 64
	s_waitcnt lgkmcnt(0)
	v_pk_mov_b32 v[44:45], v[60:61], v[82:83] op_sel:[1,0]
	v_mov_b32_e32 v61, v83
	s_waitcnt vmcnt(0)
	v_pk_mul_f32 v[60:61], v[54:55], v[60:61]
	s_nop 0
	v_pk_fma_f32 v[44:45], v[54:55], v[44:45], v[60:61] op_sel:[1,0,0] op_sel_hi:[0,1,1]
	v_mov_b32_e32 v60, v62
	v_mov_b32_e32 v61, v84
	v_pk_fma_f32 v[44:45], v[56:57], v[60:61], v[44:45] op_sel_hi:[0,1,1]
	v_mov_b32_e32 v84, v63
	ds_read_b128 v[60:63], v42 offset:512
	v_mov_b32_e32 v40, v57
	v_pk_fma_f32 v[44:45], v[40:41], v[84:85], v[44:45] op_sel_hi:[0,1,1]
	v_pk_add_f32 v[44:45], v[4:5], v[44:45]
	s_waitcnt lgkmcnt(0)
	v_mul_f32_e32 v4, v55, v61
	v_pk_fma_f32 v[4:5], v[54:55], v[60:61], v[4:5] op_sel_hi:[1,1,0]
	v_mul_f32_e32 v82, v56, v62
	v_mul_f32_e32 v84, v57, v63
	ds_read_b128 v[60:63], v42 offset:768
	s_waitcnt lgkmcnt(0)
; #define LAS __attribute__((address_space(3)))
; DI void attn_sample_task(LAS unsigned char* wl, int task, int l, ArgsP a, const bf16_t* Q, bf16_t* YB, int lane) {
;     ...
;     for (int rr = 0; rr < 3; ++rr) { const int j = rr * 64 + lane; float s[4] = {0.f, 0.f, 0.f, 0.f};
;         if (j < 132) { const float* kp = j < 128 ? ck + (size_t)j * 128 : nk + (size_t)(j - 128) * 128;
; #pragma unroll 4
;             for (int d4 = 0; d4 < 16; ++d4) { const f32x4 k4 = *(const f32x4*)(kp + 4 * d4);
; #pragma unroll
;                 for (int t = 0; t < 4; ++t) { const f32x4 q4 = *(const LAS f32x4*)(qs + t * 64 + 4 * d4); s[t] += k4[0] * q4[0] + k4[1] * q4[1] + k4[2] * q4[2] + k4[3] * q4[3]; } } }
; #pragma unroll
;         for (int t = 0; t < 4; ++t) { const bool valid = (j < 132) && (j >= t + 1) && (j <= t + 128); const float v = valid ? s[t] * 0.125f : -INFINITY;
;             if (j < 136) ps[t * 136 + j] = v; mx[t] = fmaxf(mx[t], v); } }
	v_mul_f32_e32 v40, v54, v60
	v_pk_mul_f32 v[56:57], v[56:57], v[62:63]
	v_pk_fma_f32 v[54:55], v[54:55], v[60:61], v[40:41] op_sel_hi:[1,1,0]
	v_mov_b32_e32 v5, v56
	v_mov_b32_e32 v83, v55
	v_pk_add_f32 v[4:5], v[4:5], v[82:83]
	v_mov_b32_e32 v85, v57
	v_pk_add_f32 v[4:5], v[84:85], v[4:5]
	v_mov_b32_e32 v40, v51
	v_pk_add_f32 v[54:55], v[6:7], v[4:5]
	ds_read_b128 v[4:7], v42 offset:272
	s_waitcnt lgkmcnt(0)
	v_pk_mov_b32 v[56:57], v[70:71], v[4:5] op_sel:[1,0]
	v_mov_b32_e32 v71, v5
	v_pk_mul_f32 v[4:5], v[48:49], v[70:71]
	s_nop 0
	v_pk_fma_f32 v[4:5], v[48:49], v[56:57], v[4:5] op_sel:[1,0,0] op_sel_hi:[0,1,1]
	v_mov_b32_e32 v56, v72
	v_mov_b32_e32 v57, v6
	v_pk_fma_f32 v[4:5], v[50:51], v[56:57], v[4:5] op_sel_hi:[0,1,1]
	v_mov_b32_e32 v6, v73
	v_pk_fma_f32 v[4:5], v[40:41], v[6:7], v[4:5] op_sel_hi:[0,1,1]
	v_pk_add_f32 v[44:45], v[44:45], v[4:5]
	ds_read_b128 v[4:7], v42 offset:528
	s_waitcnt lgkmcnt(0)
	v_mul_f32_e32 v40, v49, v5
	v_pk_fma_f32 v[56:57], v[48:49], v[4:5], v[40:41] op_sel_hi:[1,1,0]
	v_mul_f32_e32 v60, v50, v6
	v_mul_f32_e32 v62, v51, v7
	ds_read_b128 v[4:7], v42 offset:784
	s_waitcnt lgkmcnt(0)
	v_mul_f32_e32 v40, v48, v4
	v_pk_mul_f32 v[6:7], v[50:51], v[6:7]
	v_pk_fma_f32 v[4:5], v[48:49], v[4:5], v[40:41] op_sel_hi:[1,1,0]
	v_mov_b32_e32 v57, v6
	v_mov_b32_e32 v61, v5
	v_pk_add_f32 v[4:5], v[56:57], v[60:61]
	v_mov_b32_e32 v63, v7
	v_pk_add_f32 v[4:5], v[62:63], v[4:5]
	v_mov_b32_e32 v40, v39
	v_pk_add_f32 v[48:49], v[54:55], v[4:5]
	ds_read_b128 v[4:7], v42 offset:288
	s_waitcnt lgkmcnt(0)
	v_pk_mov_b32 v[50:51], v[74:75], v[4:5] op_sel:[1,0]
	v_mov_b32_e32 v75, v5
	v_pk_mul_f32 v[4:5], v[36:37], v[74:75]
	s_nop 0
	v_pk_fma_f32 v[4:5], v[36:37], v[50:51], v[4:5] op_sel:[1,0,0] op_sel_hi:[0,1,1]
	v_mov_b32_e32 v50, v76
	v_mov_b32_e32 v51, v6
	v_pk_fma_f32 v[4:5], v[38:39], v[50:51], v[4:5] op_sel_hi:[0,1,1]
	v_mov_b32_e32 v6, v77
	v_pk_fma_f32 v[4:5], v[40:41], v[6:7], v[4:5] op_sel_hi:[0,1,1]
	v_pk_add_f32 v[44:45], v[44:45], v[4:5]
	ds_read_b128 v[4:7], v42 offset:544
	s_waitcnt lgkmcnt(0)
	v_mul_f32_e32 v40, v37, v5
	v_pk_fma_f32 v[50:51], v[36:37], v[4:5], v[40:41] op_sel_hi:[1,1,0]
	v_mul_f32_e32 v54, v38, v6
	v_mul_f32_e32 v56, v39, v7
	ds_read_b128 v[4:7], v42 offset:800
	s_waitcnt lgkmcnt(0)
	v_pk_mul_f32 v[6:7], v[38:39], v[6:7]
	v_mul_f32_e32 v38, v36, v4
	v_pk_fma_f32 v[4:5], v[36:37], v[4:5], v[38:39] op_sel_hi:[1,1,0]
	v_mov_b32_e32 v51, v6
	v_mov_b32_e32 v55, v5
	v_pk_add_f32 v[4:5], v[50:51], v[54:55]
	v_mov_b32_e32 v57, v7
	v_pk_add_f32 v[4:5], v[56:57], v[4:5]
	s_nop 0
	v_pk_add_f32 v[48:49], v[48:49], v[4:5]
	ds_read_b128 v[4:7], v42 offset:304
	s_waitcnt lgkmcnt(0)
	v_pk_mov_b32 v[36:37], v[78:79], v[4:5] op_sel:[1,0]
	v_mov_b32_e32 v79, v5
	v_pk_mul_f32 v[4:5], v[32:33], v[78:79]
	s_nop 0
	v_pk_fma_f32 v[4:5], v[32:33], v[36:37], v[4:5] op_sel:[1,0,0] op_sel_hi:[0,1,1]
	v_mov_b32_e32 v36, v80
	v_mov_b32_e32 v37, v6
	v_pk_fma_f32 v[4:5], v[34:35], v[36:37], v[4:5] op_sel_hi:[0,1,1]
	v_mov_b32_e32 v36, v35
	v_mov_b32_e32 v6, v81
	v_pk_fma_f32 v[4:5], v[36:37], v[6:7], v[4:5] op_sel_hi:[0,1,1]
	ds_read_b128 v[36:39], v42 offset:560
	v_pk_add_f32 v[4:5], v[44:45], v[4:5]
	s_waitcnt lgkmcnt(0)
	v_mul_f32_e32 v6, v33, v37
	v_pk_fma_f32 v[6:7], v[32:33], v[36:37], v[6:7] op_sel_hi:[1,1,0]
	v_mul_f32_e32 v44, v34, v38
	v_mul_f32_e32 v50, v35, v39
	ds_read_b128 v[36:39], v42 offset:816
	s_waitcnt lgkmcnt(0)
	v_pk_mul_f32 v[34:35], v[34:35], v[38:39]
	v_mul_f32_e32 v38, v32, v36
	v_pk_fma_f32 v[32:33], v[32:33], v[36:37], v[38:39] op_sel_hi:[1,1,0]
	v_mov_b32_e32 v7, v34
	v_mov_b32_e32 v45, v33
	v_pk_add_f32 v[6:7], v[6:7], v[44:45]
	v_mov_b32_e32 v51, v35
	v_pk_add_f32 v[6:7], v[50:51], v[6:7]
	s_nop 0
	v_pk_add_f32 v[6:7], v[48:49], v[6:7]
	v_mul_f32_e32 v2, 0x3e000000, v4
	v_cndmask_b32_e64 v35, v2, v195, s[6:7]
	v_mul_f32_e32 v2, 0x3e000000, v5
	v_cndmask_b32_e64 v34, v195, v2, s[8:9]
	v_mul_f32_e32 v2, 0x3e000000, v6
	v_cndmask_b32_e64 v33, v195, v2, s[10:11]
	v_mul_f32_e32 v2, 0x3e000000, v7
	v_mov_b32_e32 v4, 0
	v_add_u32_e32 v36, 0x400, v47
	v_cndmask_b32_e64 v32, v195, v2, s[12:13]
	v_add_u32_e32 v40, 0x800, v47
	v_lshl_add_u64 v[2:3], v[16:17], 0, v[0:1]
	s_mov_b32 s2, 0
	v_mov_b32_e32 v5, v4
	v_mov_b32_e32 v6, v4
	v_mov_b32_e32 v7, v4
	ds_write2_b32 v36, v35, v34 offset1:136
	ds_write2_b32 v40, v33, v32 offset0:16 offset1:152
; #define LAS __attribute__((address_space(3)))
; DI void attn_sample_task(LAS unsigned char* wl, int task, int l, ArgsP a, const bf16_t* Q, bf16_t* YB, int lane) {
;     ...
;     for (int rr = 0; rr < 3; ++rr) { const int j = rr * 64 + lane; float s[4] = {0.f, 0.f, 0.f, 0.f};
;         if (j < 132) { const float* kp = j < 128 ? ck + (size_t)j * 128 : nk + (size_t)(j - 128) * 128;
; #pragma unroll 4
;             for (int d4 = 0; d4 < 16; ++d4) { const f32x4 k4 = *(const f32x4*)(kp + 4 * d4);
; #pragma unroll
;                 for (int t = 0; t < 4; ++t) { const f32x4 q4 = *(const LAS f32x4*)(qs + t * 64 + 4 * d4); s[t] += k4[0] * q4[0] + k4[1] * q4[1] + k4[2] * q4[2] + k4[3] * q4[3]; } } }
.LBB0_971:
	global_load_dwordx4 v[198:201], v[2:3], off offset:16
	global_load_dwordx4 v[202:205], v[2:3], off
	global_load_dwordx4 v[206:209], v[2:3], off offset:-16
	global_load_dwordx4 v[210:213], v[2:3], off offset:-32
	global_load_dwordx4 v[214:217], v[2:3], off offset:80
	global_load_dwordx4 v[218:221], v[2:3], off offset:64
	global_load_dwordx4 v[222:225], v[2:3], off offset:48
	global_load_dwordx4 v[226:229], v[2:3], off offset:32
	global_load_dwordx4 v[230:233], v[2:3], off offset:144
	global_load_dwordx4 v[234:237], v[2:3], off offset:128
	global_load_dwordx4 v[238:241], v[2:3], off offset:112
	global_load_dwordx4 v[242:245], v[2:3], off offset:96
	global_load_dwordx4 v[48:51], v[2:3], off offset:208
	global_load_dwordx4 v[54:57], v[2:3], off offset:192
	global_load_dwordx4 v[60:63], v[2:3], off offset:176
	global_load_dwordx4 v[70:73], v[2:3], off offset:160
	v_add_u32_e32 v37, s2, v43
	ds_read_b128 v[74:77], v37
	ds_read_b128 v[78:81], v37 offset:16
	ds_read_b128 v[82:85], v37 offset:32
	ds_read_b128 v[86:89], v37 offset:48
	ds_read_b128 v[90:93], v37 offset:256
	s_add_i32 s2, s2, 64
	s_waitcnt lgkmcnt(0)
	v_pk_mov_b32 v[38:39], v[74:75], v[90:91] op_sel:[1,0]
	v_mov_b32_e32 v75, v91
	s_waitcnt vmcnt(12)
	v_pk_mul_f32 v[44:45], v[210:211], v[74:75]
	s_nop 0
	v_pk_fma_f32 v[38:39], v[210:211], v[38:39], v[44:45] op_sel:[1,0,0] op_sel_hi:[0,1,1]
	v_mov_b32_e32 v44, v76
	v_mov_b32_e32 v45, v92
	v_mov_b32_e32 v92, v77
	ds_read_b128 v[74:77], v37 offset:512
	v_pk_fma_f32 v[38:39], v[212:213], v[44:45], v[38:39] op_sel_hi:[0,1,1]
	v_mov_b32_e32 v42, v213
	v_pk_fma_f32 v[38:39], v[42:43], v[92:93], v[38:39] op_sel_hi:[0,1,1]
	v_pk_add_f32 v[38:39], v[4:5], v[38:39]
	s_waitcnt lgkmcnt(0)
	v_mul_f32_e32 v4, v211, v75
	v_pk_fma_f32 v[4:5], v[210:211], v[74:75], v[4:5] op_sel_hi:[1,1,0]
	v_mul_f32_e32 v44, v212, v76
	v_mul_f32_e32 v90, v213, v77
	ds_read_b128 v[74:77], v37 offset:768
	s_waitcnt lgkmcnt(0)
	v_mul_f32_e32 v42, v210, v74
	v_pk_mul_f32 v[212:213], v[212:213], v[76:77]
	v_pk_fma_f32 v[210:211], v[210:211], v[74:75], v[42:43] op_sel_hi:[1,1,0]
	v_mov_b32_e32 v5, v212
	v_mov_b32_e32 v45, v211
	v_pk_add_f32 v[4:5], v[4:5], v[44:45]
	v_mov_b32_e32 v91, v213
	v_pk_add_f32 v[4:5], v[90:91], v[4:5]
	v_mov_b32_e32 v42, v209
	v_pk_add_f32 v[44:45], v[6:7], v[4:5]
	ds_read_b128 v[4:7], v37 offset:272
	s_waitcnt lgkmcnt(0)
	v_pk_mov_b32 v[210:211], v[78:79], v[4:5] op_sel:[1,0]
	v_mov_b32_e32 v79, v5
	v_pk_mul_f32 v[4:5], v[206:207], v[78:79]
	s_nop 0
	v_pk_fma_f32 v[4:5], v[206:207], v[210:211], v[4:5] op_sel:[1,0,0] op_sel_hi:[0,1,1]
	v_mov_b32_e32 v210, v80
	v_mov_b32_e32 v211, v6
	v_pk_fma_f32 v[4:5], v[208:209], v[210:211], v[4:5] op_sel_hi:[0,1,1]
	v_mov_b32_e32 v6, v81
	v_pk_fma_f32 v[4:5], v[42:43], v[6:7], v[4:5] op_sel_hi:[0,1,1]
	v_pk_add_f32 v[38:39], v[38:39], v[4:5]
	ds_read_b128 v[4:7], v37 offset:528
	s_waitcnt lgkmcnt(0)
	v_mul_f32_e32 v42, v207, v5
	v_pk_fma_f32 v[210:211], v[206:207], v[4:5], v[42:43] op_sel_hi:[1,1,0]
	v_mul_f32_e32 v212, v208, v6
	v_mul_f32_e32 v74, v209, v7
	ds_read_b128 v[4:7], v37 offset:784
	s_waitcnt lgkmcnt(0)
	v_mul_f32_e32 v42, v206, v4
	v_pk_mul_f32 v[6:7], v[208:209], v[6:7]
	v_pk_fma_f32 v[4:5], v[206:207], v[4:5], v[42:43] op_sel_hi:[1,1,0]
	v_mov_b32_e32 v211, v6
	v_mov_b32_e32 v213, v5
	v_pk_add_f32 v[4:5], v[210:211], v[212:213]
	v_mov_b32_e32 v75, v7
	v_pk_add_f32 v[4:5], v[74:75], v[4:5]
	v_mov_b32_e32 v42, v205
	v_pk_add_f32 v[44:45], v[44:45], v[4:5]
	ds_read_b128 v[4:7], v37 offset:288
	s_waitcnt lgkmcnt(0)
	v_pk_mov_b32 v[206:207], v[82:83], v[4:5] op_sel:[1,0]
	v_mov_b32_e32 v83, v5
	v_pk_mul_f32 v[4:5], v[202:203], v[82:83]
	s_nop 0
	v_pk_fma_f32 v[4:5], v[202:203], v[206:207], v[4:5] op_sel:[1,0,0] op_sel_hi:[0,1,1]
	v_mov_b32_e32 v206, v84
	v_mov_b32_e32 v207, v6
	v_pk_fma_f32 v[4:5], v[204:205], v[206:207], v[4:5] op_sel_hi:[0,1,1]
	v_mov_b32_e32 v6, v85
	v_pk_fma_f32 v[4:5], v[42:43], v[6:7], v[4:5] op_sel_hi:[0,1,1]
	v_pk_add_f32 v[38:39], v[38:39], v[4:5]
	ds_read_b128 v[4:7], v37 offset:544
	s_waitcnt lgkmcnt(0)
	v_mul_f32_e32 v42, v203, v5
	v_pk_fma_f32 v[206:207], v[202:203], v[4:5], v[42:43] op_sel_hi:[1,1,0]
	v_mul_f32_e32 v208, v204, v6
	v_mul_f32_e32 v210, v205, v7
	ds_read_b128 v[4:7], v37 offset:800
	s_waitcnt lgkmcnt(0)
	v_mul_f32_e32 v42, v202, v4
	v_pk_mul_f32 v[6:7], v[204:205], v[6:7]
	v_pk_fma_f32 v[4:5], v[202:203], v[4:5], v[42:43] op_sel_hi:[1,1,0]
	v_mov_b32_e32 v207, v6
	v_mov_b32_e32 v209, v5
	v_pk_add_f32 v[4:5], v[206:207], v[208:209]
	v_mov_b32_e32 v211, v7
	v_pk_add_f32 v[4:5], v[210:211], v[4:5]
	v_mov_b32_e32 v42, v201
	v_pk_add_f32 v[44:45], v[44:45], v[4:5]
	ds_read_b128 v[4:7], v37 offset:304
	s_waitcnt lgkmcnt(0)
	v_pk_mov_b32 v[202:203], v[86:87], v[4:5] op_sel:[1,0]
	v_mov_b32_e32 v87, v5
	v_pk_mul_f32 v[4:5], v[198:199], v[86:87]
	s_nop 0
	v_pk_fma_f32 v[4:5], v[198:199], v[202:203], v[4:5] op_sel:[1,0,0] op_sel_hi:[0,1,1]
	v_mov_b32_e32 v202, v88
	v_mov_b32_e32 v203, v6
	v_pk_fma_f32 v[4:5], v[200:201], v[202:203], v[4:5] op_sel_hi:[0,1,1]
	ds_read_b128 v[202:205], v37 offset:560
	v_mov_b32_e32 v6, v89
	v_pk_fma_f32 v[4:5], v[42:43], v[6:7], v[4:5] op_sel_hi:[0,1,1]
	v_pk_add_f32 v[4:5], v[38:39], v[4:5]
	s_waitcnt lgkmcnt(0)
	v_mul_f32_e32 v6, v199, v203
	v_pk_fma_f32 v[6:7], v[198:199], v[202:203], v[6:7] op_sel_hi:[1,1,0]
	v_mul_f32_e32 v38, v200, v204
	v_mul_f32_e32 v206, v201, v205
	ds_read_b128 v[202:205], v37 offset:816
	s_waitcnt lgkmcnt(0)
; #define LAS __attribute__((address_space(3)))
; DI void attn_sample_task(LAS unsigned char* wl, int task, int l, ArgsP a, const bf16_t* Q, bf16_t* YB, int lane) {
;     ...
;     for (int rr = 0; rr < 3; ++rr) { const int j = rr * 64 + lane; float s[4] = {0.f, 0.f, 0.f, 0.f};
;         if (j < 132) { const float* kp = j < 128 ? ck + (size_t)j * 128 : nk + (size_t)(j - 128) * 128;
; #pragma unroll 4
;             for (int d4 = 0; d4 < 16; ++d4) { const f32x4 k4 = *(const f32x4*)(kp + 4 * d4);
; #pragma unroll
;                 for (int t = 0; t < 4; ++t) { const f32x4 q4 = *(const LAS f32x4*)(qs + t * 64 + 4 * d4); s[t] += k4[0] * q4[0] + k4[1] * q4[1] + k4[2] * q4[2] + k4[3] * q4[3]; } } }
	v_mul_f32_e32 v42, v198, v202
	v_pk_mul_f32 v[200:201], v[200:201], v[204:205]
	v_pk_fma_f32 v[198:199], v[198:199], v[202:203], v[42:43] op_sel_hi:[1,1,0]
	v_mov_b32_e32 v7, v200
	v_mov_b32_e32 v39, v199
	v_pk_add_f32 v[6:7], v[6:7], v[38:39]
	v_mov_b32_e32 v207, v201
	v_pk_add_f32 v[6:7], v[206:207], v[6:7]
	s_nop 0
	v_pk_add_f32 v[6:7], v[44:45], v[6:7]
	v_add_u32_e32 v37, s2, v43
	ds_read_b128 v[74:77], v37
	ds_read_b128 v[78:81], v37 offset:16
	ds_read_b128 v[82:85], v37 offset:32
	ds_read_b128 v[86:89], v37 offset:48
	ds_read_b128 v[90:93], v37 offset:256
	s_add_i32 s2, s2, 64
	s_waitcnt lgkmcnt(0)
	v_pk_mov_b32 v[38:39], v[74:75], v[90:91] op_sel:[1,0]
	v_mov_b32_e32 v75, v91
	s_waitcnt vmcnt(8)
	v_pk_mul_f32 v[44:45], v[226:227], v[74:75]
	s_nop 0
	v_pk_fma_f32 v[38:39], v[226:227], v[38:39], v[44:45] op_sel:[1,0,0] op_sel_hi:[0,1,1]
	v_mov_b32_e32 v44, v76
	v_mov_b32_e32 v45, v92
	v_mov_b32_e32 v92, v77
	ds_read_b128 v[74:77], v37 offset:512
	v_pk_fma_f32 v[38:39], v[228:229], v[44:45], v[38:39] op_sel_hi:[0,1,1]
	v_mov_b32_e32 v42, v229
	v_pk_fma_f32 v[38:39], v[42:43], v[92:93], v[38:39] op_sel_hi:[0,1,1]
	v_pk_add_f32 v[38:39], v[4:5], v[38:39]
	s_waitcnt lgkmcnt(0)
	v_mul_f32_e32 v4, v227, v75
	v_pk_fma_f32 v[4:5], v[226:227], v[74:75], v[4:5] op_sel_hi:[1,1,0]
	v_mul_f32_e32 v44, v228, v76
	v_mul_f32_e32 v90, v229, v77
	ds_read_b128 v[74:77], v37 offset:768
	s_waitcnt lgkmcnt(0)
	v_mul_f32_e32 v42, v226, v74
	v_pk_mul_f32 v[228:229], v[228:229], v[76:77]
	v_pk_fma_f32 v[226:227], v[226:227], v[74:75], v[42:43] op_sel_hi:[1,1,0]
	v_mov_b32_e32 v5, v228
	v_mov_b32_e32 v45, v227
	v_pk_add_f32 v[4:5], v[4:5], v[44:45]
	v_mov_b32_e32 v91, v229
	v_pk_add_f32 v[4:5], v[90:91], v[4:5]
	v_mov_b32_e32 v42, v225
	v_pk_add_f32 v[44:45], v[6:7], v[4:5]
	ds_read_b128 v[4:7], v37 offset:272
	s_waitcnt lgkmcnt(0)
	v_pk_mov_b32 v[226:227], v[78:79], v[4:5] op_sel:[1,0]
	v_mov_b32_e32 v79, v5
	v_pk_mul_f32 v[4:5], v[222:223], v[78:79]
	s_nop 0
	v_pk_fma_f32 v[4:5], v[222:223], v[226:227], v[4:5] op_sel:[1,0,0] op_sel_hi:[0,1,1]
	v_mov_b32_e32 v226, v80
	v_mov_b32_e32 v227, v6
	v_pk_fma_f32 v[4:5], v[224:225], v[226:227], v[4:5] op_sel_hi:[0,1,1]
	v_mov_b32_e32 v6, v81
	v_pk_fma_f32 v[4:5], v[42:43], v[6:7], v[4:5] op_sel_hi:[0,1,1]
	v_pk_add_f32 v[38:39], v[38:39], v[4:5]
	ds_read_b128 v[4:7], v37 offset:528
	s_waitcnt lgkmcnt(0)
	v_mul_f32_e32 v42, v223, v5
	v_pk_fma_f32 v[226:227], v[222:223], v[4:5], v[42:43] op_sel_hi:[1,1,0]
	v_mul_f32_e32 v228, v224, v6
	v_mul_f32_e32 v74, v225, v7
	ds_read_b128 v[4:7], v37 offset:784
	s_waitcnt lgkmcnt(0)
	v_mul_f32_e32 v42, v222, v4
	v_pk_mul_f32 v[6:7], v[224:225], v[6:7]
	v_pk_fma_f32 v[4:5], v[222:223], v[4:5], v[42:43] op_sel_hi:[1,1,0]
	v_mov_b32_e32 v227, v6
	v_mov_b32_e32 v229, v5
	v_pk_add_f32 v[4:5], v[226:227], v[228:229]
	v_mov_b32_e32 v75, v7
	v_pk_add_f32 v[4:5], v[74:75], v[4:5]
	v_mov_b32_e32 v42, v221
	v_pk_add_f32 v[44:45], v[44:45], v[4:5]
	ds_read_b128 v[4:7], v37 offset:288
	s_waitcnt lgkmcnt(0)
	v_pk_mov_b32 v[222:223], v[82:83], v[4:5] op_sel:[1,0]
	v_mov_b32_e32 v83, v5
	v_pk_mul_f32 v[4:5], v[218:219], v[82:83]
	s_nop 0
	v_pk_fma_f32 v[4:5], v[218:219], v[222:223], v[4:5] op_sel:[1,0,0] op_sel_hi:[0,1,1]
	v_mov_b32_e32 v222, v84
	v_mov_b32_e32 v223, v6
	v_pk_fma_f32 v[4:5], v[220:221], v[222:223], v[4:5] op_sel_hi:[0,1,1]
	v_mov_b32_e32 v6, v85
	v_pk_fma_f32 v[4:5], v[42:43], v[6:7], v[4:5] op_sel_hi:[0,1,1]
	v_pk_add_f32 v[38:39], v[38:39], v[4:5]
	ds_read_b128 v[4:7], v37 offset:544
	s_waitcnt lgkmcnt(0)
	v_mul_f32_e32 v42, v219, v5
	v_pk_fma_f32 v[222:223], v[218:219], v[4:5], v[42:43] op_sel_hi:[1,1,0]
	v_mul_f32_e32 v224, v220, v6
	v_mul_f32_e32 v226, v221, v7
	ds_read_b128 v[4:7], v37 offset:800
	s_waitcnt lgkmcnt(0)
	v_mul_f32_e32 v42, v218, v4
	v_pk_mul_f32 v[6:7], v[220:221], v[6:7]
	v_pk_fma_f32 v[4:5], v[218:219], v[4:5], v[42:43] op_sel_hi:[1,1,0]
	v_mov_b32_e32 v223, v6
	v_mov_b32_e32 v225, v5
	v_pk_add_f32 v[4:5], v[222:223], v[224:225]
	v_mov_b32_e32 v227, v7
	v_pk_add_f32 v[4:5], v[226:227], v[4:5]
	v_mov_b32_e32 v42, v217
	v_pk_add_f32 v[44:45], v[44:45], v[4:5]
	ds_read_b128 v[4:7], v37 offset:304
	s_waitcnt lgkmcnt(0)
	v_pk_mov_b32 v[218:219], v[86:87], v[4:5] op_sel:[1,0]
	v_mov_b32_e32 v87, v5
	v_pk_mul_f32 v[4:5], v[214:215], v[86:87]
	s_nop 0
	v_pk_fma_f32 v[4:5], v[214:215], v[218:219], v[4:5] op_sel:[1,0,0] op_sel_hi:[0,1,1]
	v_mov_b32_e32 v218, v88
	v_mov_b32_e32 v219, v6
	v_pk_fma_f32 v[4:5], v[216:217], v[218:219], v[4:5] op_sel_hi:[0,1,1]
	ds_read_b128 v[218:221], v37 offset:560
	v_mov_b32_e32 v6, v89
	v_pk_fma_f32 v[4:5], v[42:43], v[6:7], v[4:5] op_sel_hi:[0,1,1]
	v_pk_add_f32 v[4:5], v[38:39], v[4:5]
	s_waitcnt lgkmcnt(0)
	v_mul_f32_e32 v6, v215, v219
	v_pk_fma_f32 v[6:7], v[214:215], v[218:219], v[6:7] op_sel_hi:[1,1,0]
	v_mul_f32_e32 v38, v216, v220
	v_mul_f32_e32 v222, v217, v221
	ds_read_b128 v[218:221], v37 offset:816
	s_waitcnt lgkmcnt(0)
	v_mul_f32_e32 v42, v214, v218
	v_pk_mul_f32 v[216:217], v[216:217], v[220:221]
	v_pk_fma_f32 v[214:215], v[214:215], v[218:219], v[42:43] op_sel_hi:[1,1,0]
	v_mov_b32_e32 v7, v216
	v_mov_b32_e32 v39, v215
	v_pk_add_f32 v[6:7], v[6:7], v[38:39]
	v_mov_b32_e32 v223, v217
	v_pk_add_f32 v[6:7], v[222:223], v[6:7]
	s_nop 0
	v_pk_add_f32 v[6:7], v[44:45], v[6:7]
	v_add_u32_e32 v37, s2, v43
	ds_read_b128 v[74:77], v37
	ds_read_b128 v[78:81], v37 offset:16
	ds_read_b128 v[82:85], v37 offset:32
	ds_read_b128 v[86:89], v37 offset:48
	ds_read_b128 v[90:93], v37 offset:256
	s_add_i32 s2, s2, 64
	s_waitcnt lgkmcnt(0)
	v_pk_mov_b32 v[38:39], v[74:75], v[90:91] op_sel:[1,0]
	v_mov_b32_e32 v75, v91
	s_waitcnt vmcnt(4)
; #define LAS __attribute__((address_space(3)))
; DI void attn_sample_task(LAS unsigned char* wl, int task, int l, ArgsP a, const bf16_t* Q, bf16_t* YB, int lane) {
;     ...
;     for (int rr = 0; rr < 3; ++rr) { const int j = rr * 64 + lane; float s[4] = {0.f, 0.f, 0.f, 0.f};
;         if (j < 132) { const float* kp = j < 128 ? ck + (size_t)j * 128 : nk + (size_t)(j - 128) * 128;
; #pragma unroll 4
;             for (int d4 = 0; d4 < 16; ++d4) { const f32x4 k4 = *(const f32x4*)(kp + 4 * d4);
; #pragma unroll
;                 for (int t = 0; t < 4; ++t) { const f32x4 q4 = *(const LAS f32x4*)(qs + t * 64 + 4 * d4); s[t] += k4[0] * q4[0] + k4[1] * q4[1] + k4[2] * q4[2] + k4[3] * q4[3]; } } }
	v_pk_mul_f32 v[44:45], v[242:243], v[74:75]
	s_nop 0
	v_pk_fma_f32 v[38:39], v[242:243], v[38:39], v[44:45] op_sel:[1,0,0] op_sel_hi:[0,1,1]
	v_mov_b32_e32 v44, v76
	v_mov_b32_e32 v45, v92
	v_mov_b32_e32 v92, v77
	ds_read_b128 v[74:77], v37 offset:512
	v_pk_fma_f32 v[38:39], v[244:245], v[44:45], v[38:39] op_sel_hi:[0,1,1]
	v_mov_b32_e32 v42, v245
	v_pk_fma_f32 v[38:39], v[42:43], v[92:93], v[38:39] op_sel_hi:[0,1,1]
	v_pk_add_f32 v[38:39], v[4:5], v[38:39]
	s_waitcnt lgkmcnt(0)
	v_mul_f32_e32 v4, v243, v75
	v_pk_fma_f32 v[4:5], v[242:243], v[74:75], v[4:5] op_sel_hi:[1,1,0]
	v_mul_f32_e32 v44, v244, v76
	v_mul_f32_e32 v90, v245, v77
	ds_read_b128 v[74:77], v37 offset:768
	s_waitcnt lgkmcnt(0)
	v_mul_f32_e32 v42, v242, v74
	v_pk_mul_f32 v[244:245], v[244:245], v[76:77]
	v_pk_fma_f32 v[242:243], v[242:243], v[74:75], v[42:43] op_sel_hi:[1,1,0]
	v_mov_b32_e32 v5, v244
	v_mov_b32_e32 v45, v243
	v_pk_add_f32 v[4:5], v[4:5], v[44:45]
	v_mov_b32_e32 v91, v245
	v_pk_add_f32 v[4:5], v[90:91], v[4:5]
	v_mov_b32_e32 v42, v241
	v_pk_add_f32 v[44:45], v[6:7], v[4:5]
	ds_read_b128 v[4:7], v37 offset:272
	s_waitcnt lgkmcnt(0)
	v_pk_mov_b32 v[242:243], v[78:79], v[4:5] op_sel:[1,0]
	v_mov_b32_e32 v79, v5
	v_pk_mul_f32 v[4:5], v[238:239], v[78:79]
	s_nop 0
	v_pk_fma_f32 v[4:5], v[238:239], v[242:243], v[4:5] op_sel:[1,0,0] op_sel_hi:[0,1,1]
	v_mov_b32_e32 v242, v80
	v_mov_b32_e32 v243, v6
	v_pk_fma_f32 v[4:5], v[240:241], v[242:243], v[4:5] op_sel_hi:[0,1,1]
	v_mov_b32_e32 v6, v81
	v_pk_fma_f32 v[4:5], v[42:43], v[6:7], v[4:5] op_sel_hi:[0,1,1]
	v_pk_add_f32 v[38:39], v[38:39], v[4:5]
	ds_read_b128 v[4:7], v37 offset:528
	s_waitcnt lgkmcnt(0)
	v_mul_f32_e32 v42, v239, v5
	v_pk_fma_f32 v[242:243], v[238:239], v[4:5], v[42:43] op_sel_hi:[1,1,0]
	v_mul_f32_e32 v244, v240, v6
	v_mul_f32_e32 v74, v241, v7
	ds_read_b128 v[4:7], v37 offset:784
	s_waitcnt lgkmcnt(0)
	v_mul_f32_e32 v42, v238, v4
	v_pk_mul_f32 v[6:7], v[240:241], v[6:7]
	v_pk_fma_f32 v[4:5], v[238:239], v[4:5], v[42:43] op_sel_hi:[1,1,0]
	v_mov_b32_e32 v243, v6
	v_mov_b32_e32 v245, v5
	v_pk_add_f32 v[4:5], v[242:243], v[244:245]
	v_mov_b32_e32 v75, v7
	v_pk_add_f32 v[4:5], v[74:75], v[4:5]
	v_mov_b32_e32 v42, v237
	v_pk_add_f32 v[44:45], v[44:45], v[4:5]
	ds_read_b128 v[4:7], v37 offset:288
	s_waitcnt lgkmcnt(0)
	v_pk_mov_b32 v[238:239], v[82:83], v[4:5] op_sel:[1,0]
	v_mov_b32_e32 v83, v5
	v_pk_mul_f32 v[4:5], v[234:235], v[82:83]
	s_nop 0
	v_pk_fma_f32 v[4:5], v[234:235], v[238:239], v[4:5] op_sel:[1,0,0] op_sel_hi:[0,1,1]
	v_mov_b32_e32 v238, v84
	v_mov_b32_e32 v239, v6
	v_pk_fma_f32 v[4:5], v[236:237], v[238:239], v[4:5] op_sel_hi:[0,1,1]
	v_mov_b32_e32 v6, v85
	v_pk_fma_f32 v[4:5], v[42:43], v[6:7], v[4:5] op_sel_hi:[0,1,1]
	v_pk_add_f32 v[38:39], v[38:39], v[4:5]
	ds_read_b128 v[4:7], v37 offset:544
	s_waitcnt lgkmcnt(0)
	v_mul_f32_e32 v42, v235, v5
	v_pk_fma_f32 v[238:239], v[234:235], v[4:5], v[42:43] op_sel_hi:[1,1,0]
	v_mul_f32_e32 v240, v236, v6
	v_mul_f32_e32 v242, v237, v7
	ds_read_b128 v[4:7], v37 offset:800
	s_waitcnt lgkmcnt(0)
	v_mul_f32_e32 v42, v234, v4
	v_pk_mul_f32 v[6:7], v[236:237], v[6:7]
	v_pk_fma_f32 v[4:5], v[234:235], v[4:5], v[42:43] op_sel_hi:[1,1,0]
	v_mov_b32_e32 v239, v6
	v_mov_b32_e32 v241, v5
	v_pk_add_f32 v[4:5], v[238:239], v[240:241]
	v_mov_b32_e32 v243, v7
	v_pk_add_f32 v[4:5], v[242:243], v[4:5]
	v_mov_b32_e32 v42, v233
	v_pk_add_f32 v[44:45], v[44:45], v[4:5]
	ds_read_b128 v[4:7], v37 offset:304
	s_waitcnt lgkmcnt(0)
	v_pk_mov_b32 v[234:235], v[86:87], v[4:5] op_sel:[1,0]
	v_mov_b32_e32 v87, v5
	v_pk_mul_f32 v[4:5], v[230:231], v[86:87]
	s_nop 0
	v_pk_fma_f32 v[4:5], v[230:231], v[234:235], v[4:5] op_sel:[1,0,0] op_sel_hi:[0,1,1]
	v_mov_b32_e32 v234, v88
	v_mov_b32_e32 v235, v6
	v_pk_fma_f32 v[4:5], v[232:233], v[234:235], v[4:5] op_sel_hi:[0,1,1]
	ds_read_b128 v[234:237], v37 offset:560
	v_mov_b32_e32 v6, v89
	v_pk_fma_f32 v[4:5], v[42:43], v[6:7], v[4:5] op_sel_hi:[0,1,1]
	v_pk_add_f32 v[4:5], v[38:39], v[4:5]
	s_waitcnt lgkmcnt(0)
	v_mul_f32_e32 v6, v231, v235
	v_pk_fma_f32 v[6:7], v[230:231], v[234:235], v[6:7] op_sel_hi:[1,1,0]
	v_mul_f32_e32 v38, v232, v236
	v_mul_f32_e32 v238, v233, v237
	ds_read_b128 v[234:237], v37 offset:816
	s_waitcnt lgkmcnt(0)
	v_mul_f32_e32 v42, v230, v234
	v_pk_mul_f32 v[232:233], v[232:233], v[236:237]
	v_pk_fma_f32 v[230:231], v[230:231], v[234:235], v[42:43] op_sel_hi:[1,1,0]
	v_mov_b32_e32 v7, v232
	v_mov_b32_e32 v39, v231
	v_pk_add_f32 v[6:7], v[6:7], v[38:39]
	v_mov_b32_e32 v239, v233
	v_pk_add_f32 v[6:7], v[238:239], v[6:7]
	s_nop 0
	v_pk_add_f32 v[6:7], v[44:45], v[6:7]
	v_add_u32_e32 v37, s2, v43
	ds_read_b128 v[74:77], v37
	ds_read_b128 v[78:81], v37 offset:16
	ds_read_b128 v[82:85], v37 offset:32
	ds_read_b128 v[86:89], v37 offset:48
	ds_read_b128 v[90:93], v37 offset:256
	s_add_i32 s2, s2, 64
	s_waitcnt lgkmcnt(0)
	v_pk_mov_b32 v[38:39], v[74:75], v[90:91] op_sel:[1,0]
	v_mov_b32_e32 v75, v91
	s_waitcnt vmcnt(0)
	v_pk_mul_f32 v[44:45], v[70:71], v[74:75]
	s_nop 0
	v_pk_fma_f32 v[38:39], v[70:71], v[38:39], v[44:45] op_sel:[1,0,0] op_sel_hi:[0,1,1]
	v_mov_b32_e32 v44, v76
	v_mov_b32_e32 v45, v92
	v_mov_b32_e32 v92, v77
	ds_read_b128 v[74:77], v37 offset:512
	v_pk_fma_f32 v[38:39], v[72:73], v[44:45], v[38:39] op_sel_hi:[0,1,1]
	v_mov_b32_e32 v42, v73
	v_pk_fma_f32 v[38:39], v[42:43], v[92:93], v[38:39] op_sel_hi:[0,1,1]
	v_pk_add_f32 v[38:39], v[4:5], v[38:39]
	s_waitcnt lgkmcnt(0)
	v_mul_f32_e32 v4, v71, v75
	v_pk_fma_f32 v[4:5], v[70:71], v[74:75], v[4:5] op_sel_hi:[1,1,0]
	v_mul_f32_e32 v44, v72, v76
	v_mul_f32_e32 v90, v73, v77
	ds_read_b128 v[74:77], v37 offset:768
	s_waitcnt lgkmcnt(0)
; #define LAS __attribute__((address_space(3)))
; DI void attn_sample_task(LAS unsigned char* wl, int task, int l, ArgsP a, const bf16_t* Q, bf16_t* YB, int lane) {
;     ...
;     for (int rr = 0; rr < 3; ++rr) { const int j = rr * 64 + lane; float s[4] = {0.f, 0.f, 0.f, 0.f};
;         if (j < 132) { const float* kp = j < 128 ? ck + (size_t)j * 128 : nk + (size_t)(j - 128) * 128;
; #pragma unroll 4
;             for (int d4 = 0; d4 < 16; ++d4) { const f32x4 k4 = *(const f32x4*)(kp + 4 * d4);
; #pragma unroll
;                 for (int t = 0; t < 4; ++t) { const f32x4 q4 = *(const LAS f32x4*)(qs + t * 64 + 4 * d4); s[t] += k4[0] * q4[0] + k4[1] * q4[1] + k4[2] * q4[2] + k4[3] * q4[3]; } } }
; #pragma unroll
;         for (int t = 0; t < 4; ++t) { const bool valid = (j < 132) && (j >= t + 1) && (j <= t + 128); const float v = valid ? s[t] * 0.125f : -INFINITY;
;             if (j < 136) ps[t * 136 + j] = v; mx[t] = fmaxf(mx[t], v); } }
	v_mul_f32_e32 v42, v70, v74
	v_pk_mul_f32 v[72:73], v[72:73], v[76:77]
	v_pk_fma_f32 v[70:71], v[70:71], v[74:75], v[42:43] op_sel_hi:[1,1,0]
	v_mov_b32_e32 v5, v72
	v_mov_b32_e32 v45, v71
	v_pk_add_f32 v[4:5], v[4:5], v[44:45]
	v_mov_b32_e32 v91, v73
	v_pk_add_f32 v[4:5], v[90:91], v[4:5]
	v_mov_b32_e32 v42, v63
	v_pk_add_f32 v[44:45], v[6:7], v[4:5]
	ds_read_b128 v[4:7], v37 offset:272
	s_waitcnt lgkmcnt(0)
	v_pk_mov_b32 v[70:71], v[78:79], v[4:5] op_sel:[1,0]
	v_mov_b32_e32 v79, v5
	v_pk_mul_f32 v[4:5], v[60:61], v[78:79]
	s_nop 0
	v_pk_fma_f32 v[4:5], v[60:61], v[70:71], v[4:5] op_sel:[1,0,0] op_sel_hi:[0,1,1]
	v_mov_b32_e32 v70, v80
	v_mov_b32_e32 v71, v6
	v_pk_fma_f32 v[4:5], v[62:63], v[70:71], v[4:5] op_sel_hi:[0,1,1]
	v_mov_b32_e32 v6, v81
	v_pk_fma_f32 v[4:5], v[42:43], v[6:7], v[4:5] op_sel_hi:[0,1,1]
	v_pk_add_f32 v[38:39], v[38:39], v[4:5]
	ds_read_b128 v[4:7], v37 offset:528
	s_waitcnt lgkmcnt(0)
	v_mul_f32_e32 v42, v61, v5
	v_pk_fma_f32 v[70:71], v[60:61], v[4:5], v[42:43] op_sel_hi:[1,1,0]
	v_mul_f32_e32 v72, v62, v6
	v_mul_f32_e32 v74, v63, v7
	ds_read_b128 v[4:7], v37 offset:784
	s_waitcnt lgkmcnt(0)
	v_mul_f32_e32 v42, v60, v4
	v_pk_mul_f32 v[6:7], v[62:63], v[6:7]
	v_pk_fma_f32 v[4:5], v[60:61], v[4:5], v[42:43] op_sel_hi:[1,1,0]
	v_mov_b32_e32 v71, v6
	v_mov_b32_e32 v73, v5
	v_pk_add_f32 v[4:5], v[70:71], v[72:73]
	v_mov_b32_e32 v75, v7
	v_pk_add_f32 v[4:5], v[74:75], v[4:5]
	v_mov_b32_e32 v42, v57
	v_pk_add_f32 v[44:45], v[44:45], v[4:5]
	ds_read_b128 v[4:7], v37 offset:288
	s_waitcnt lgkmcnt(0)
	v_pk_mov_b32 v[60:61], v[82:83], v[4:5] op_sel:[1,0]
	v_mov_b32_e32 v83, v5
	v_pk_mul_f32 v[4:5], v[54:55], v[82:83]
	s_nop 0
	v_pk_fma_f32 v[4:5], v[54:55], v[60:61], v[4:5] op_sel:[1,0,0] op_sel_hi:[0,1,1]
	v_mov_b32_e32 v60, v84
	v_mov_b32_e32 v61, v6
	v_pk_fma_f32 v[4:5], v[56:57], v[60:61], v[4:5] op_sel_hi:[0,1,1]
	v_mov_b32_e32 v6, v85
	v_pk_fma_f32 v[4:5], v[42:43], v[6:7], v[4:5] op_sel_hi:[0,1,1]
	v_pk_add_f32 v[38:39], v[38:39], v[4:5]
	ds_read_b128 v[4:7], v37 offset:544
	s_waitcnt lgkmcnt(0)
	v_mul_f32_e32 v42, v55, v5
	v_pk_fma_f32 v[60:61], v[54:55], v[4:5], v[42:43] op_sel_hi:[1,1,0]
	v_mul_f32_e32 v62, v56, v6
	v_mul_f32_e32 v70, v57, v7
	ds_read_b128 v[4:7], v37 offset:800
	s_waitcnt lgkmcnt(0)
	v_mul_f32_e32 v42, v54, v4
	v_pk_mul_f32 v[6:7], v[56:57], v[6:7]
	v_pk_fma_f32 v[4:5], v[54:55], v[4:5], v[42:43] op_sel_hi:[1,1,0]
	v_mov_b32_e32 v61, v6
	v_mov_b32_e32 v63, v5
	v_pk_add_f32 v[4:5], v[60:61], v[62:63]
	v_mov_b32_e32 v71, v7
	v_pk_add_f32 v[4:5], v[70:71], v[4:5]
	v_mov_b32_e32 v42, v51
	v_pk_add_f32 v[44:45], v[44:45], v[4:5]
	ds_read_b128 v[4:7], v37 offset:304
	s_waitcnt lgkmcnt(0)
	v_pk_mov_b32 v[54:55], v[86:87], v[4:5] op_sel:[1,0]
	v_mov_b32_e32 v87, v5
	v_pk_mul_f32 v[4:5], v[48:49], v[86:87]
	s_nop 0
	v_pk_fma_f32 v[4:5], v[48:49], v[54:55], v[4:5] op_sel:[1,0,0] op_sel_hi:[0,1,1]
	v_mov_b32_e32 v54, v88
	v_mov_b32_e32 v55, v6
	v_pk_fma_f32 v[4:5], v[50:51], v[54:55], v[4:5] op_sel_hi:[0,1,1]
	ds_read_b128 v[54:57], v37 offset:560
	v_mov_b32_e32 v6, v89
	v_pk_fma_f32 v[4:5], v[42:43], v[6:7], v[4:5] op_sel_hi:[0,1,1]
	v_pk_add_f32 v[4:5], v[38:39], v[4:5]
	s_waitcnt lgkmcnt(0)
	v_mul_f32_e32 v6, v49, v55
	v_pk_fma_f32 v[6:7], v[48:49], v[54:55], v[6:7] op_sel_hi:[1,1,0]
	v_mul_f32_e32 v38, v50, v56
	v_mul_f32_e32 v60, v51, v57
	ds_read_b128 v[54:57], v37 offset:816
	s_waitcnt lgkmcnt(0)
	v_mul_f32_e32 v42, v48, v54
	v_pk_mul_f32 v[50:51], v[50:51], v[56:57]
	v_pk_fma_f32 v[48:49], v[48:49], v[54:55], v[42:43] op_sel_hi:[1,1,0]
	v_mov_b32_e32 v7, v50
	v_mov_b32_e32 v39, v49
	v_pk_add_f32 v[6:7], v[6:7], v[38:39]
	v_mov_b32_e32 v61, v51
	v_pk_add_f32 v[6:7], v[60:61], v[6:7]
	s_nop 0
	v_pk_add_f32 v[6:7], v[44:45], v[6:7]
	v_mul_f32_e32 v39, 0x3e000000, v4
	v_mul_f32_e32 v38, 0x3e000000, v5
	ds_write2_b32 v36, v39, v38 offset0:64 offset1:200
	v_mul_f32_e32 v37, 0x3e000000, v6
	v_mul_f32_e32 v36, 0x3e000000, v7
	v_mov_b32_e32 v5, 0
	v_mov_b32_e32 v4, 0
	v_mov_b32_e32 v7, 0
	v_mov_b32_e32 v6, 0
	ds_write2_b32 v40, v37, v36 offset0:80 offset1:216
	s_and_saveexec_b64 s[2:3], s[14:15]
	s_cbranch_execz .LBB0_975
	v_mov_b32_e32 v6, 0
	v_lshl_add_u64 v[2:3], v[18:19], 0, v[0:1]
	s_mov_b32 s22, 0
	v_mov_b32_e32 v7, v6
	v_mov_b32_e32 v4, v6
	v_mov_b32_e32 v5, v6
; #define LAS __attribute__((address_space(3)))
; DI void attn_sample_task(LAS unsigned char* wl, int task, int l, ArgsP a, const bf16_t* Q, bf16_t* YB, int lane) {
;     ...
;     for (int rr = 0; rr < 3; ++rr) { const int j = rr * 64 + lane; float s[4] = {0.f, 0.f, 0.f, 0.f};
;         if (j < 132) { const float* kp = j < 128 ? ck + (size_t)j * 128 : nk + (size_t)(j - 128) * 128;
; #pragma unroll 4
;             for (int d4 = 0; d4 < 16; ++d4) { const f32x4 k4 = *(const f32x4*)(kp + 4 * d4);
; #pragma unroll
;                 for (int t = 0; t < 4; ++t) { const f32x4 q4 = *(const LAS f32x4*)(qs + t * 64 + 4 * d4); s[t] += k4[0] * q4[0] + k4[1] * q4[1] + k4[2] * q4[2] + k4[3] * q4[3]; } } }
.LBB0_974:
	global_load_dwordx4 v[198:201], v[2:3], off offset:16
	global_load_dwordx4 v[202:205], v[2:3], off
	global_load_dwordx4 v[206:209], v[2:3], off offset:-16
	global_load_dwordx4 v[210:213], v[2:3], off offset:-32
	global_load_dwordx4 v[214:217], v[2:3], off offset:80
	global_load_dwordx4 v[218:221], v[2:3], off offset:64
	global_load_dwordx4 v[222:225], v[2:3], off offset:48
	global_load_dwordx4 v[226:229], v[2:3], off offset:32
	global_load_dwordx4 v[230:233], v[2:3], off offset:144
	global_load_dwordx4 v[234:237], v[2:3], off offset:128
	global_load_dwordx4 v[238:241], v[2:3], off offset:112
	global_load_dwordx4 v[242:245], v[2:3], off offset:96
	global_load_dwordx4 v[48:51], v[2:3], off offset:208
	global_load_dwordx4 v[54:57], v[2:3], off offset:192
	global_load_dwordx4 v[60:63], v[2:3], off offset:176
	global_load_dwordx4 v[70:73], v[2:3], off offset:160
	v_add_u32_e32 v42, s22, v43
	ds_read_b128 v[74:77], v42
	ds_read_b128 v[78:81], v42 offset:16
	ds_read_b128 v[82:85], v42 offset:32
	ds_read_b128 v[86:89], v42 offset:48
	ds_read_b128 v[90:93], v42 offset:256
	s_add_i32 s22, s22, 64
	s_waitcnt lgkmcnt(0)
	v_pk_mov_b32 v[44:45], v[74:75], v[90:91] op_sel:[1,0]
	v_mov_b32_e32 v75, v91
	s_waitcnt vmcnt(12)
	v_pk_mul_f32 v[74:75], v[210:211], v[74:75]
	s_nop 0
	v_pk_fma_f32 v[44:45], v[210:211], v[44:45], v[74:75] op_sel:[1,0,0] op_sel_hi:[0,1,1]
	v_mov_b32_e32 v74, v76
	v_mov_b32_e32 v75, v92
	v_pk_fma_f32 v[44:45], v[212:213], v[74:75], v[44:45] op_sel_hi:[0,1,1]
	v_mov_b32_e32 v92, v77
	ds_read_b128 v[74:77], v42 offset:512
	v_mov_b32_e32 v40, v213
	v_pk_fma_f32 v[44:45], v[40:41], v[92:93], v[44:45] op_sel_hi:[0,1,1]
	v_pk_add_f32 v[44:45], v[6:7], v[44:45]
	s_waitcnt lgkmcnt(0)
	v_mul_f32_e32 v6, v211, v75
	v_pk_fma_f32 v[6:7], v[210:211], v[74:75], v[6:7] op_sel_hi:[1,1,0]
	v_mul_f32_e32 v90, v212, v76
	v_mul_f32_e32 v92, v213, v77
	ds_read_b128 v[74:77], v42 offset:768
	s_waitcnt lgkmcnt(0)
	v_mul_f32_e32 v40, v210, v74
	v_pk_mul_f32 v[212:213], v[212:213], v[76:77]
	v_pk_fma_f32 v[210:211], v[210:211], v[74:75], v[40:41] op_sel_hi:[1,1,0]
	v_mov_b32_e32 v7, v212
	v_mov_b32_e32 v91, v211
	v_pk_add_f32 v[6:7], v[6:7], v[90:91]
	v_mov_b32_e32 v93, v213
	v_pk_add_f32 v[6:7], v[92:93], v[6:7]
	v_mov_b32_e32 v40, v209
	v_pk_add_f32 v[210:211], v[4:5], v[6:7]
	ds_read_b128 v[4:7], v42 offset:272
	s_waitcnt lgkmcnt(0)
	v_pk_mov_b32 v[212:213], v[78:79], v[4:5] op_sel:[1,0]
	v_mov_b32_e32 v79, v5
	v_pk_mul_f32 v[4:5], v[206:207], v[78:79]
	s_nop 0
	v_pk_fma_f32 v[4:5], v[206:207], v[212:213], v[4:5] op_sel:[1,0,0] op_sel_hi:[0,1,1]
	v_mov_b32_e32 v212, v80
	v_mov_b32_e32 v213, v6
	v_pk_fma_f32 v[4:5], v[208:209], v[212:213], v[4:5] op_sel_hi:[0,1,1]
	v_mov_b32_e32 v6, v81
	v_pk_fma_f32 v[4:5], v[40:41], v[6:7], v[4:5] op_sel_hi:[0,1,1]
	v_pk_add_f32 v[44:45], v[44:45], v[4:5]
	ds_read_b128 v[4:7], v42 offset:528
	s_waitcnt lgkmcnt(0)
	v_mul_f32_e32 v40, v207, v5
	v_pk_fma_f32 v[212:213], v[206:207], v[4:5], v[40:41] op_sel_hi:[1,1,0]
	v_mul_f32_e32 v74, v208, v6
	v_mul_f32_e32 v76, v209, v7
	ds_read_b128 v[4:7], v42 offset:784
	s_waitcnt lgkmcnt(0)
	v_mul_f32_e32 v40, v206, v4
	v_pk_mul_f32 v[6:7], v[208:209], v[6:7]
	v_pk_fma_f32 v[4:5], v[206:207], v[4:5], v[40:41] op_sel_hi:[1,1,0]
	v_mov_b32_e32 v213, v6
	v_mov_b32_e32 v75, v5
	v_pk_add_f32 v[4:5], v[212:213], v[74:75]
	v_mov_b32_e32 v77, v7
	v_pk_add_f32 v[4:5], v[76:77], v[4:5]
	v_mov_b32_e32 v40, v205
	v_pk_add_f32 v[206:207], v[210:211], v[4:5]
	ds_read_b128 v[4:7], v42 offset:288
	s_waitcnt lgkmcnt(0)
	v_pk_mov_b32 v[208:209], v[82:83], v[4:5] op_sel:[1,0]
	v_mov_b32_e32 v83, v5
	v_pk_mul_f32 v[4:5], v[202:203], v[82:83]
	s_nop 0
	v_pk_fma_f32 v[4:5], v[202:203], v[208:209], v[4:5] op_sel:[1,0,0] op_sel_hi:[0,1,1]
	v_mov_b32_e32 v208, v84
	v_mov_b32_e32 v209, v6
	v_pk_fma_f32 v[4:5], v[204:205], v[208:209], v[4:5] op_sel_hi:[0,1,1]
	v_mov_b32_e32 v6, v85
	v_pk_fma_f32 v[4:5], v[40:41], v[6:7], v[4:5] op_sel_hi:[0,1,1]
	v_pk_add_f32 v[44:45], v[44:45], v[4:5]
	ds_read_b128 v[4:7], v42 offset:544
	s_waitcnt lgkmcnt(0)
	v_mul_f32_e32 v40, v203, v5
	v_pk_fma_f32 v[208:209], v[202:203], v[4:5], v[40:41] op_sel_hi:[1,1,0]
	v_mul_f32_e32 v210, v204, v6
	v_mul_f32_e32 v212, v205, v7
	ds_read_b128 v[4:7], v42 offset:800
	s_waitcnt lgkmcnt(0)
	v_mul_f32_e32 v40, v202, v4
	v_pk_mul_f32 v[6:7], v[204:205], v[6:7]
	v_pk_fma_f32 v[4:5], v[202:203], v[4:5], v[40:41] op_sel_hi:[1,1,0]
	v_mov_b32_e32 v209, v6
	v_mov_b32_e32 v211, v5
	v_pk_add_f32 v[4:5], v[208:209], v[210:211]
	v_mov_b32_e32 v213, v7
	v_pk_add_f32 v[4:5], v[212:213], v[4:5]
	v_mov_b32_e32 v40, v201
	v_pk_add_f32 v[206:207], v[206:207], v[4:5]
	ds_read_b128 v[4:7], v42 offset:304
	s_waitcnt lgkmcnt(0)
	v_pk_mov_b32 v[202:203], v[86:87], v[4:5] op_sel:[1,0]
	v_mov_b32_e32 v87, v5
	v_pk_mul_f32 v[4:5], v[198:199], v[86:87]
	s_nop 0
	v_pk_fma_f32 v[4:5], v[198:199], v[202:203], v[4:5] op_sel:[1,0,0] op_sel_hi:[0,1,1]
	v_mov_b32_e32 v202, v88
	v_mov_b32_e32 v203, v6
	v_pk_fma_f32 v[4:5], v[200:201], v[202:203], v[4:5] op_sel_hi:[0,1,1]
	ds_read_b128 v[202:205], v42 offset:560
	v_mov_b32_e32 v6, v89
	v_pk_fma_f32 v[4:5], v[40:41], v[6:7], v[4:5] op_sel_hi:[0,1,1]
	v_pk_add_f32 v[6:7], v[44:45], v[4:5]
	s_waitcnt lgkmcnt(0)
	v_mul_f32_e32 v4, v199, v203
	v_pk_fma_f32 v[4:5], v[198:199], v[202:203], v[4:5] op_sel_hi:[1,1,0]
	v_mul_f32_e32 v44, v200, v204
	v_mul_f32_e32 v208, v201, v205
	ds_read_b128 v[202:205], v42 offset:816
	s_waitcnt lgkmcnt(0)
; #define LAS __attribute__((address_space(3)))
; DI void attn_sample_task(LAS unsigned char* wl, int task, int l, ArgsP a, const bf16_t* Q, bf16_t* YB, int lane) {
;     ...
;     for (int rr = 0; rr < 3; ++rr) { const int j = rr * 64 + lane; float s[4] = {0.f, 0.f, 0.f, 0.f};
;         if (j < 132) { const float* kp = j < 128 ? ck + (size_t)j * 128 : nk + (size_t)(j - 128) * 128;
; #pragma unroll 4
;             for (int d4 = 0; d4 < 16; ++d4) { const f32x4 k4 = *(const f32x4*)(kp + 4 * d4);
; #pragma unroll
;                 for (int t = 0; t < 4; ++t) { const f32x4 q4 = *(const LAS f32x4*)(qs + t * 64 + 4 * d4); s[t] += k4[0] * q4[0] + k4[1] * q4[1] + k4[2] * q4[2] + k4[3] * q4[3]; } } }
	v_mul_f32_e32 v40, v198, v202
	v_pk_mul_f32 v[200:201], v[200:201], v[204:205]
	v_pk_fma_f32 v[198:199], v[198:199], v[202:203], v[40:41] op_sel_hi:[1,1,0]
	v_mov_b32_e32 v5, v200
	v_mov_b32_e32 v45, v199
	v_pk_add_f32 v[4:5], v[4:5], v[44:45]
	v_mov_b32_e32 v209, v201
	v_pk_add_f32 v[4:5], v[208:209], v[4:5]
	s_nop 0
	v_pk_add_f32 v[4:5], v[206:207], v[4:5]
	v_add_u32_e32 v42, s22, v43
	ds_read_b128 v[74:77], v42
	ds_read_b128 v[78:81], v42 offset:16
	ds_read_b128 v[82:85], v42 offset:32
	ds_read_b128 v[86:89], v42 offset:48
	ds_read_b128 v[90:93], v42 offset:256
	s_add_i32 s22, s22, 64
	s_waitcnt lgkmcnt(0)
	v_pk_mov_b32 v[44:45], v[74:75], v[90:91] op_sel:[1,0]
	v_mov_b32_e32 v75, v91
	s_waitcnt vmcnt(8)
	v_pk_mul_f32 v[74:75], v[226:227], v[74:75]
	s_nop 0
	v_pk_fma_f32 v[44:45], v[226:227], v[44:45], v[74:75] op_sel:[1,0,0] op_sel_hi:[0,1,1]
	v_mov_b32_e32 v74, v76
	v_mov_b32_e32 v75, v92
	v_pk_fma_f32 v[44:45], v[228:229], v[74:75], v[44:45] op_sel_hi:[0,1,1]
	v_mov_b32_e32 v92, v77
	ds_read_b128 v[74:77], v42 offset:512
	v_mov_b32_e32 v40, v229
	v_pk_fma_f32 v[44:45], v[40:41], v[92:93], v[44:45] op_sel_hi:[0,1,1]
	v_pk_add_f32 v[44:45], v[6:7], v[44:45]
	s_waitcnt lgkmcnt(0)
	v_mul_f32_e32 v6, v227, v75
	v_pk_fma_f32 v[6:7], v[226:227], v[74:75], v[6:7] op_sel_hi:[1,1,0]
	v_mul_f32_e32 v90, v228, v76
	v_mul_f32_e32 v92, v229, v77
	ds_read_b128 v[74:77], v42 offset:768
	s_waitcnt lgkmcnt(0)
	v_mul_f32_e32 v40, v226, v74
	v_pk_mul_f32 v[228:229], v[228:229], v[76:77]
	v_pk_fma_f32 v[226:227], v[226:227], v[74:75], v[40:41] op_sel_hi:[1,1,0]
	v_mov_b32_e32 v7, v228
	v_mov_b32_e32 v91, v227
	v_pk_add_f32 v[6:7], v[6:7], v[90:91]
	v_mov_b32_e32 v93, v229
	v_pk_add_f32 v[6:7], v[92:93], v[6:7]
	v_mov_b32_e32 v40, v225
	v_pk_add_f32 v[226:227], v[4:5], v[6:7]
	ds_read_b128 v[4:7], v42 offset:272
	s_waitcnt lgkmcnt(0)
	v_pk_mov_b32 v[228:229], v[78:79], v[4:5] op_sel:[1,0]
	v_mov_b32_e32 v79, v5
	v_pk_mul_f32 v[4:5], v[222:223], v[78:79]
	s_nop 0
	v_pk_fma_f32 v[4:5], v[222:223], v[228:229], v[4:5] op_sel:[1,0,0] op_sel_hi:[0,1,1]
	v_mov_b32_e32 v228, v80
	v_mov_b32_e32 v229, v6
	v_pk_fma_f32 v[4:5], v[224:225], v[228:229], v[4:5] op_sel_hi:[0,1,1]
	v_mov_b32_e32 v6, v81
	v_pk_fma_f32 v[4:5], v[40:41], v[6:7], v[4:5] op_sel_hi:[0,1,1]
	v_pk_add_f32 v[44:45], v[44:45], v[4:5]
	ds_read_b128 v[4:7], v42 offset:528
	s_waitcnt lgkmcnt(0)
	v_mul_f32_e32 v40, v223, v5
	v_pk_fma_f32 v[228:229], v[222:223], v[4:5], v[40:41] op_sel_hi:[1,1,0]
	v_mul_f32_e32 v74, v224, v6
	v_mul_f32_e32 v76, v225, v7
	ds_read_b128 v[4:7], v42 offset:784
	s_waitcnt lgkmcnt(0)
	v_mul_f32_e32 v40, v222, v4
	v_pk_mul_f32 v[6:7], v[224:225], v[6:7]
	v_pk_fma_f32 v[4:5], v[222:223], v[4:5], v[40:41] op_sel_hi:[1,1,0]
	v_mov_b32_e32 v229, v6
	v_mov_b32_e32 v75, v5
	v_pk_add_f32 v[4:5], v[228:229], v[74:75]
	v_mov_b32_e32 v77, v7
	v_pk_add_f32 v[4:5], v[76:77], v[4:5]
	v_mov_b32_e32 v40, v221
	v_pk_add_f32 v[222:223], v[226:227], v[4:5]
	ds_read_b128 v[4:7], v42 offset:288
	s_waitcnt lgkmcnt(0)
	v_pk_mov_b32 v[224:225], v[82:83], v[4:5] op_sel:[1,0]
	v_mov_b32_e32 v83, v5
	v_pk_mul_f32 v[4:5], v[218:219], v[82:83]
	s_nop 0
	v_pk_fma_f32 v[4:5], v[218:219], v[224:225], v[4:5] op_sel:[1,0,0] op_sel_hi:[0,1,1]
	v_mov_b32_e32 v224, v84
	v_mov_b32_e32 v225, v6
	v_pk_fma_f32 v[4:5], v[220:221], v[224:225], v[4:5] op_sel_hi:[0,1,1]
	v_mov_b32_e32 v6, v85
	v_pk_fma_f32 v[4:5], v[40:41], v[6:7], v[4:5] op_sel_hi:[0,1,1]
	v_pk_add_f32 v[44:45], v[44:45], v[4:5]
	ds_read_b128 v[4:7], v42 offset:544
	s_waitcnt lgkmcnt(0)
	v_mul_f32_e32 v40, v219, v5
	v_pk_fma_f32 v[224:225], v[218:219], v[4:5], v[40:41] op_sel_hi:[1,1,0]
	v_mul_f32_e32 v226, v220, v6
	v_mul_f32_e32 v228, v221, v7
	ds_read_b128 v[4:7], v42 offset:800
	s_waitcnt lgkmcnt(0)
	v_mul_f32_e32 v40, v218, v4
	v_pk_mul_f32 v[6:7], v[220:221], v[6:7]
	v_pk_fma_f32 v[4:5], v[218:219], v[4:5], v[40:41] op_sel_hi:[1,1,0]
	v_mov_b32_e32 v225, v6
	v_mov_b32_e32 v227, v5
	v_pk_add_f32 v[4:5], v[224:225], v[226:227]
	v_mov_b32_e32 v229, v7
	v_pk_add_f32 v[4:5], v[228:229], v[4:5]
	v_mov_b32_e32 v40, v217
	v_pk_add_f32 v[222:223], v[222:223], v[4:5]
	ds_read_b128 v[4:7], v42 offset:304
	s_waitcnt lgkmcnt(0)
	v_pk_mov_b32 v[218:219], v[86:87], v[4:5] op_sel:[1,0]
	v_mov_b32_e32 v87, v5
	v_pk_mul_f32 v[4:5], v[214:215], v[86:87]
	s_nop 0
	v_pk_fma_f32 v[4:5], v[214:215], v[218:219], v[4:5] op_sel:[1,0,0] op_sel_hi:[0,1,1]
	v_mov_b32_e32 v218, v88
	v_mov_b32_e32 v219, v6
	v_pk_fma_f32 v[4:5], v[216:217], v[218:219], v[4:5] op_sel_hi:[0,1,1]
	ds_read_b128 v[218:221], v42 offset:560
	v_mov_b32_e32 v6, v89
	v_pk_fma_f32 v[4:5], v[40:41], v[6:7], v[4:5] op_sel_hi:[0,1,1]
	v_pk_add_f32 v[6:7], v[44:45], v[4:5]
	s_waitcnt lgkmcnt(0)
	v_mul_f32_e32 v4, v215, v219
	v_pk_fma_f32 v[4:5], v[214:215], v[218:219], v[4:5] op_sel_hi:[1,1,0]
	v_mul_f32_e32 v44, v216, v220
	v_mul_f32_e32 v224, v217, v221
	ds_read_b128 v[218:221], v42 offset:816
	s_waitcnt lgkmcnt(0)
	v_mul_f32_e32 v40, v214, v218
	v_pk_mul_f32 v[216:217], v[216:217], v[220:221]
	v_pk_fma_f32 v[214:215], v[214:215], v[218:219], v[40:41] op_sel_hi:[1,1,0]
	v_mov_b32_e32 v5, v216
	v_mov_b32_e32 v45, v215
	v_pk_add_f32 v[4:5], v[4:5], v[44:45]
	v_mov_b32_e32 v225, v217
	v_pk_add_f32 v[4:5], v[224:225], v[4:5]
	s_nop 0
	v_pk_add_f32 v[4:5], v[222:223], v[4:5]
	v_add_u32_e32 v42, s22, v43
	ds_read_b128 v[74:77], v42
	ds_read_b128 v[78:81], v42 offset:16
	ds_read_b128 v[82:85], v42 offset:32
	ds_read_b128 v[86:89], v42 offset:48
	ds_read_b128 v[90:93], v42 offset:256
	s_add_i32 s22, s22, 64
	s_waitcnt lgkmcnt(0)
	v_pk_mov_b32 v[44:45], v[74:75], v[90:91] op_sel:[1,0]
	v_mov_b32_e32 v75, v91
	s_waitcnt vmcnt(4)
; #define LAS __attribute__((address_space(3)))
; DI void attn_sample_task(LAS unsigned char* wl, int task, int l, ArgsP a, const bf16_t* Q, bf16_t* YB, int lane) {
;     ...
;     for (int rr = 0; rr < 3; ++rr) { const int j = rr * 64 + lane; float s[4] = {0.f, 0.f, 0.f, 0.f};
;         if (j < 132) { const float* kp = j < 128 ? ck + (size_t)j * 128 : nk + (size_t)(j - 128) * 128;
; #pragma unroll 4
;             for (int d4 = 0; d4 < 16; ++d4) { const f32x4 k4 = *(const f32x4*)(kp + 4 * d4);
; #pragma unroll
;                 for (int t = 0; t < 4; ++t) { const f32x4 q4 = *(const LAS f32x4*)(qs + t * 64 + 4 * d4); s[t] += k4[0] * q4[0] + k4[1] * q4[1] + k4[2] * q4[2] + k4[3] * q4[3]; } } }
	v_pk_mul_f32 v[74:75], v[242:243], v[74:75]
	s_nop 0
	v_pk_fma_f32 v[44:45], v[242:243], v[44:45], v[74:75] op_sel:[1,0,0] op_sel_hi:[0,1,1]
	v_mov_b32_e32 v74, v76
	v_mov_b32_e32 v75, v92
	v_pk_fma_f32 v[44:45], v[244:245], v[74:75], v[44:45] op_sel_hi:[0,1,1]
	v_mov_b32_e32 v92, v77
	ds_read_b128 v[74:77], v42 offset:512
	v_mov_b32_e32 v40, v245
	v_pk_fma_f32 v[44:45], v[40:41], v[92:93], v[44:45] op_sel_hi:[0,1,1]
	v_pk_add_f32 v[44:45], v[6:7], v[44:45]
	s_waitcnt lgkmcnt(0)
	v_mul_f32_e32 v6, v243, v75
	v_pk_fma_f32 v[6:7], v[242:243], v[74:75], v[6:7] op_sel_hi:[1,1,0]
	v_mul_f32_e32 v90, v244, v76
	v_mul_f32_e32 v92, v245, v77
	ds_read_b128 v[74:77], v42 offset:768
	s_waitcnt lgkmcnt(0)
	v_mul_f32_e32 v40, v242, v74
	v_pk_mul_f32 v[244:245], v[244:245], v[76:77]
	v_pk_fma_f32 v[242:243], v[242:243], v[74:75], v[40:41] op_sel_hi:[1,1,0]
	v_mov_b32_e32 v7, v244
	v_mov_b32_e32 v91, v243
	v_pk_add_f32 v[6:7], v[6:7], v[90:91]
	v_mov_b32_e32 v93, v245
	v_pk_add_f32 v[6:7], v[92:93], v[6:7]
	v_mov_b32_e32 v40, v241
	v_pk_add_f32 v[242:243], v[4:5], v[6:7]
	ds_read_b128 v[4:7], v42 offset:272
	s_waitcnt lgkmcnt(0)
	v_pk_mov_b32 v[244:245], v[78:79], v[4:5] op_sel:[1,0]
	v_mov_b32_e32 v79, v5
	v_pk_mul_f32 v[4:5], v[238:239], v[78:79]
	s_nop 0
	v_pk_fma_f32 v[4:5], v[238:239], v[244:245], v[4:5] op_sel:[1,0,0] op_sel_hi:[0,1,1]
	v_mov_b32_e32 v244, v80
	v_mov_b32_e32 v245, v6
	v_pk_fma_f32 v[4:5], v[240:241], v[244:245], v[4:5] op_sel_hi:[0,1,1]
	v_mov_b32_e32 v6, v81
	v_pk_fma_f32 v[4:5], v[40:41], v[6:7], v[4:5] op_sel_hi:[0,1,1]
	v_pk_add_f32 v[44:45], v[44:45], v[4:5]
	ds_read_b128 v[4:7], v42 offset:528
	s_waitcnt lgkmcnt(0)
	v_mul_f32_e32 v40, v239, v5
	v_pk_fma_f32 v[244:245], v[238:239], v[4:5], v[40:41] op_sel_hi:[1,1,0]
	v_mul_f32_e32 v74, v240, v6
	v_mul_f32_e32 v76, v241, v7
	ds_read_b128 v[4:7], v42 offset:784
	s_waitcnt lgkmcnt(0)
	v_mul_f32_e32 v40, v238, v4
	v_pk_mul_f32 v[6:7], v[240:241], v[6:7]
	v_pk_fma_f32 v[4:5], v[238:239], v[4:5], v[40:41] op_sel_hi:[1,1,0]
	v_mov_b32_e32 v245, v6
	v_mov_b32_e32 v75, v5
	v_pk_add_f32 v[4:5], v[244:245], v[74:75]
	v_mov_b32_e32 v77, v7
	v_pk_add_f32 v[4:5], v[76:77], v[4:5]
	v_mov_b32_e32 v40, v237
	v_pk_add_f32 v[238:239], v[242:243], v[4:5]
	ds_read_b128 v[4:7], v42 offset:288
	s_waitcnt lgkmcnt(0)
	v_pk_mov_b32 v[240:241], v[82:83], v[4:5] op_sel:[1,0]
	v_mov_b32_e32 v83, v5
	v_pk_mul_f32 v[4:5], v[234:235], v[82:83]
	s_nop 0
	v_pk_fma_f32 v[4:5], v[234:235], v[240:241], v[4:5] op_sel:[1,0,0] op_sel_hi:[0,1,1]
	v_mov_b32_e32 v240, v84
	v_mov_b32_e32 v241, v6
	v_pk_fma_f32 v[4:5], v[236:237], v[240:241], v[4:5] op_sel_hi:[0,1,1]
	v_mov_b32_e32 v6, v85
	v_pk_fma_f32 v[4:5], v[40:41], v[6:7], v[4:5] op_sel_hi:[0,1,1]
	v_pk_add_f32 v[44:45], v[44:45], v[4:5]
	ds_read_b128 v[4:7], v42 offset:544
	s_waitcnt lgkmcnt(0)
	v_mul_f32_e32 v40, v235, v5
	v_pk_fma_f32 v[240:241], v[234:235], v[4:5], v[40:41] op_sel_hi:[1,1,0]
	v_mul_f32_e32 v242, v236, v6
	v_mul_f32_e32 v244, v237, v7
	ds_read_b128 v[4:7], v42 offset:800
	s_waitcnt lgkmcnt(0)
	v_mul_f32_e32 v40, v234, v4
	v_pk_mul_f32 v[6:7], v[236:237], v[6:7]
	v_pk_fma_f32 v[4:5], v[234:235], v[4:5], v[40:41] op_sel_hi:[1,1,0]
	v_mov_b32_e32 v241, v6
	v_mov_b32_e32 v243, v5
	v_pk_add_f32 v[4:5], v[240:241], v[242:243]
	v_mov_b32_e32 v245, v7
	v_pk_add_f32 v[4:5], v[244:245], v[4:5]
	v_mov_b32_e32 v40, v233
	v_pk_add_f32 v[238:239], v[238:239], v[4:5]
	ds_read_b128 v[4:7], v42 offset:304
	s_waitcnt lgkmcnt(0)
	v_pk_mov_b32 v[234:235], v[86:87], v[4:5] op_sel:[1,0]
	v_mov_b32_e32 v87, v5
	v_pk_mul_f32 v[4:5], v[230:231], v[86:87]
	s_nop 0
	v_pk_fma_f32 v[4:5], v[230:231], v[234:235], v[4:5] op_sel:[1,0,0] op_sel_hi:[0,1,1]
	v_mov_b32_e32 v234, v88
	v_mov_b32_e32 v235, v6
	v_pk_fma_f32 v[4:5], v[232:233], v[234:235], v[4:5] op_sel_hi:[0,1,1]
	ds_read_b128 v[234:237], v42 offset:560
	v_mov_b32_e32 v6, v89
	v_pk_fma_f32 v[4:5], v[40:41], v[6:7], v[4:5] op_sel_hi:[0,1,1]
	v_pk_add_f32 v[6:7], v[44:45], v[4:5]
	s_waitcnt lgkmcnt(0)
	v_mul_f32_e32 v4, v231, v235
	v_pk_fma_f32 v[4:5], v[230:231], v[234:235], v[4:5] op_sel_hi:[1,1,0]
	v_mul_f32_e32 v44, v232, v236
	v_mul_f32_e32 v240, v233, v237
	ds_read_b128 v[234:237], v42 offset:816
	s_waitcnt lgkmcnt(0)
	v_mul_f32_e32 v40, v230, v234
	v_pk_mul_f32 v[232:233], v[232:233], v[236:237]
	v_pk_fma_f32 v[230:231], v[230:231], v[234:235], v[40:41] op_sel_hi:[1,1,0]
	v_mov_b32_e32 v5, v232
	v_mov_b32_e32 v45, v231
	v_pk_add_f32 v[4:5], v[4:5], v[44:45]
	v_mov_b32_e32 v241, v233
	v_pk_add_f32 v[4:5], v[240:241], v[4:5]
	s_nop 0
	v_pk_add_f32 v[4:5], v[238:239], v[4:5]
	v_add_u32_e32 v42, s22, v43
	ds_read_b128 v[74:77], v42
	ds_read_b128 v[78:81], v42 offset:16
	ds_read_b128 v[82:85], v42 offset:32
	ds_read_b128 v[86:89], v42 offset:48
	ds_read_b128 v[90:93], v42 offset:256
	s_add_i32 s22, s22, 64
	s_waitcnt lgkmcnt(0)
; #define LAS __attribute__((address_space(3)))
; DI void attn_sample_task(LAS unsigned char* wl, int task, int l, ArgsP a, const bf16_t* Q, bf16_t* YB, int lane) {
;     ...
;     for (int rr = 0; rr < 3; ++rr) { const int j = rr * 64 + lane; float s[4] = {0.f, 0.f, 0.f, 0.f};
;         if (j < 132) { const float* kp = j < 128 ? ck + (size_t)j * 128 : nk + (size_t)(j - 128) * 128;
; #pragma unroll 4
;             for (int d4 = 0; d4 < 16; ++d4) { const f32x4 k4 = *(const f32x4*)(kp + 4 * d4);
; #pragma unroll
;                 for (int t = 0; t < 4; ++t) { const f32x4 q4 = *(const LAS f32x4*)(qs + t * 64 + 4 * d4); s[t] += k4[0] * q4[0] + k4[1] * q4[1] + k4[2] * q4[2] + k4[3] * q4[3]; } } }
	v_pk_mov_b32 v[44:45], v[74:75], v[90:91] op_sel:[1,0]
	v_mov_b32_e32 v75, v91
	s_waitcnt vmcnt(0)
	v_pk_mul_f32 v[74:75], v[70:71], v[74:75]
	s_nop 0
	v_pk_fma_f32 v[44:45], v[70:71], v[44:45], v[74:75] op_sel:[1,0,0] op_sel_hi:[0,1,1]
	v_mov_b32_e32 v74, v76
	v_mov_b32_e32 v75, v92
	v_pk_fma_f32 v[44:45], v[72:73], v[74:75], v[44:45] op_sel_hi:[0,1,1]
	v_mov_b32_e32 v92, v77
	ds_read_b128 v[74:77], v42 offset:512
	v_mov_b32_e32 v40, v73
	v_pk_fma_f32 v[44:45], v[40:41], v[92:93], v[44:45] op_sel_hi:[0,1,1]
	v_pk_add_f32 v[44:45], v[6:7], v[44:45]
	s_waitcnt lgkmcnt(0)
	v_mul_f32_e32 v6, v71, v75
	v_pk_fma_f32 v[6:7], v[70:71], v[74:75], v[6:7] op_sel_hi:[1,1,0]
	v_mul_f32_e32 v90, v72, v76
	v_mul_f32_e32 v92, v73, v77
	ds_read_b128 v[74:77], v42 offset:768
	s_waitcnt lgkmcnt(0)
	v_mul_f32_e32 v40, v70, v74
	v_pk_mul_f32 v[72:73], v[72:73], v[76:77]
	v_pk_fma_f32 v[70:71], v[70:71], v[74:75], v[40:41] op_sel_hi:[1,1,0]
	v_mov_b32_e32 v7, v72
	v_mov_b32_e32 v91, v71
	v_pk_add_f32 v[6:7], v[6:7], v[90:91]
	v_mov_b32_e32 v93, v73
	v_pk_add_f32 v[6:7], v[92:93], v[6:7]
	v_mov_b32_e32 v40, v63
	v_pk_add_f32 v[70:71], v[4:5], v[6:7]
	ds_read_b128 v[4:7], v42 offset:272
	s_waitcnt lgkmcnt(0)
	v_pk_mov_b32 v[72:73], v[78:79], v[4:5] op_sel:[1,0]
	v_mov_b32_e32 v79, v5
	v_pk_mul_f32 v[4:5], v[60:61], v[78:79]
	s_nop 0
	v_pk_fma_f32 v[4:5], v[60:61], v[72:73], v[4:5] op_sel:[1,0,0] op_sel_hi:[0,1,1]
	v_mov_b32_e32 v72, v80
	v_mov_b32_e32 v73, v6
	v_pk_fma_f32 v[4:5], v[62:63], v[72:73], v[4:5] op_sel_hi:[0,1,1]
	v_mov_b32_e32 v6, v81
	v_pk_fma_f32 v[4:5], v[40:41], v[6:7], v[4:5] op_sel_hi:[0,1,1]
	v_pk_add_f32 v[44:45], v[44:45], v[4:5]
	ds_read_b128 v[4:7], v42 offset:528
	s_waitcnt lgkmcnt(0)
	v_mul_f32_e32 v40, v61, v5
	v_pk_fma_f32 v[72:73], v[60:61], v[4:5], v[40:41] op_sel_hi:[1,1,0]
	v_mul_f32_e32 v74, v62, v6
	v_mul_f32_e32 v76, v63, v7
	ds_read_b128 v[4:7], v42 offset:784
	s_waitcnt lgkmcnt(0)
	v_mul_f32_e32 v40, v60, v4
	v_pk_mul_f32 v[6:7], v[62:63], v[6:7]
	v_pk_fma_f32 v[4:5], v[60:61], v[4:5], v[40:41] op_sel_hi:[1,1,0]
	v_mov_b32_e32 v73, v6
	v_mov_b32_e32 v75, v5
	v_pk_add_f32 v[4:5], v[72:73], v[74:75]
	v_mov_b32_e32 v77, v7
	v_pk_add_f32 v[4:5], v[76:77], v[4:5]
	v_mov_b32_e32 v40, v57
	v_pk_add_f32 v[60:61], v[70:71], v[4:5]
	ds_read_b128 v[4:7], v42 offset:288
	s_waitcnt lgkmcnt(0)
	v_pk_mov_b32 v[62:63], v[82:83], v[4:5] op_sel:[1,0]
	v_mov_b32_e32 v83, v5
	v_pk_mul_f32 v[4:5], v[54:55], v[82:83]
	s_nop 0
	v_pk_fma_f32 v[4:5], v[54:55], v[62:63], v[4:5] op_sel:[1,0,0] op_sel_hi:[0,1,1]
	v_mov_b32_e32 v62, v84
	v_mov_b32_e32 v63, v6
	v_pk_fma_f32 v[4:5], v[56:57], v[62:63], v[4:5] op_sel_hi:[0,1,1]
	v_mov_b32_e32 v6, v85
	v_pk_fma_f32 v[4:5], v[40:41], v[6:7], v[4:5] op_sel_hi:[0,1,1]
	v_pk_add_f32 v[44:45], v[44:45], v[4:5]
	ds_read_b128 v[4:7], v42 offset:544
	s_waitcnt lgkmcnt(0)
	v_mul_f32_e32 v40, v55, v5
	v_pk_fma_f32 v[62:63], v[54:55], v[4:5], v[40:41] op_sel_hi:[1,1,0]
	v_mul_f32_e32 v70, v56, v6
	v_mul_f32_e32 v72, v57, v7
	ds_read_b128 v[4:7], v42 offset:800
	s_waitcnt lgkmcnt(0)
	v_mul_f32_e32 v40, v54, v4
	v_pk_mul_f32 v[6:7], v[56:57], v[6:7]
	v_pk_fma_f32 v[4:5], v[54:55], v[4:5], v[40:41] op_sel_hi:[1,1,0]
	v_mov_b32_e32 v63, v6
	v_mov_b32_e32 v71, v5
	v_pk_add_f32 v[4:5], v[62:63], v[70:71]
	v_mov_b32_e32 v73, v7
	v_pk_add_f32 v[4:5], v[72:73], v[4:5]
	v_mov_b32_e32 v40, v51
	v_pk_add_f32 v[60:61], v[60:61], v[4:5]
	ds_read_b128 v[4:7], v42 offset:304
	s_waitcnt lgkmcnt(0)
	v_pk_mov_b32 v[54:55], v[86:87], v[4:5] op_sel:[1,0]
	v_mov_b32_e32 v87, v5
	v_pk_mul_f32 v[4:5], v[48:49], v[86:87]
	s_nop 0
	v_pk_fma_f32 v[4:5], v[48:49], v[54:55], v[4:5] op_sel:[1,0,0] op_sel_hi:[0,1,1]
	v_mov_b32_e32 v54, v88
	v_mov_b32_e32 v55, v6
	v_pk_fma_f32 v[4:5], v[50:51], v[54:55], v[4:5] op_sel_hi:[0,1,1]
	ds_read_b128 v[54:57], v42 offset:560
	v_mov_b32_e32 v6, v89
	v_pk_fma_f32 v[4:5], v[40:41], v[6:7], v[4:5] op_sel_hi:[0,1,1]
	v_pk_add_f32 v[6:7], v[44:45], v[4:5]
	s_waitcnt lgkmcnt(0)
	v_mul_f32_e32 v4, v49, v55
	v_pk_fma_f32 v[4:5], v[48:49], v[54:55], v[4:5] op_sel_hi:[1,1,0]
	v_mul_f32_e32 v44, v50, v56
	v_mul_f32_e32 v62, v51, v57
	ds_read_b128 v[54:57], v42 offset:816
	s_waitcnt lgkmcnt(0)
	v_mul_f32_e32 v40, v48, v54
	v_pk_mul_f32 v[50:51], v[50:51], v[56:57]
	v_pk_fma_f32 v[48:49], v[48:49], v[54:55], v[40:41] op_sel_hi:[1,1,0]
	v_mov_b32_e32 v5, v50
	v_mov_b32_e32 v45, v49
	v_pk_add_f32 v[4:5], v[4:5], v[44:45]
	v_mov_b32_e32 v63, v51
	v_pk_add_f32 v[4:5], v[62:63], v[4:5]
	s_nop 0
	v_pk_add_f32 v[4:5], v[60:61], v[4:5]
